# GEMM K-loops: first half-iteration peeled with SrcC=0 on first-touch MFMAs; the 128 v_mov accumulator zeroing per tile removed
# speedup vs baseline: 1.0063x; 1.0001x over previous
; template <class Epi, bool ALIGN_EPI = true>
; __device__ __forceinline__ void gemm_phase(PG8_LAS unsigned char* lds, const Gemm g, const StaticOrder& S, const Epi& E) {
;     ...
;         const bool has_next = S.next(ui + 1, nxt);
;         const char* nA = has_next ? (const char*)g.A + (size_t)nxt.pm * tstepA + (size_t)nxt.ks * ksA : cA; const char* nB = has_next ? (const char*)g.Bt + (size_t)nxt.pn * tstepB + (size_t)nxt.ks * ksA : cB;
;         for (int t = 0; t < nt; t += 2) {
;             const bool last = (t == nt - 2);
;             const char* a1 = cA + (size_t)(t + 1) * kstep;
;             const char* a2 = last ? nA : cA + (size_t)(t + 2) * kstep; const char* b2 = last ? nB : cB + (size_t)(t + 2) * kstep;
;             const char* a3 = a2 + kstep; const char* b3 = b2 + kstep;
.LBB0_438:
	s_ashr_i32 s23, s22, 31
	s_lshl_b64 s[24:25], s[22:23], 19
	s_add_u32 s24, s36, s24
	s_addc_u32 s25, s37, s25
	s_and_b64 s[26:27], s[4:5], exec
	s_cselect_b32 s3, s25, s9
	s_cselect_b32 s7, s24, s8
	s_ashr_i32 s21, s20, 31
	s_lshl_b64 s[26:27], s[20:21], 19
	s_add_u32 s26, s38, s26
	s_addc_u32 s27, s39, s27
	s_and_b64 s[30:31], s[4:5], exec
	s_cselect_b32 s21, s27, s29
	s_cselect_b32 s23, s26, s28
	s_add_u32 s8, s8, 0x40080
	s_addc_u32 s9, s9, 0
	s_add_u32 s50, s28, 0x100
	s_addc_u32 s51, s29, 0
	s_mov_b32 s52, -2
; #define PG8_STAGE(bufoff, gbase, voff) do { _Pragma("unroll") for (int _i = 0; _i < 2; ++_i) \
;         __builtin_amdgcn_global_load_lds((const unsigned*)((const char*)(gbase) + (voff)[_i]), (PG8_LAS unsigned*)(lds + (bufoff) + ldsw + _i * 8192), 16, 0, 0); } while (0)
; #define PG8_LDA(dst, b, h) do { _Pragma("unroll") for (int m = 0; m < 4; ++m) _Pragma("unroll") for (int k = 0; k < 2; ++k) dst[m][k] = *(const PG8_LAS bf16x8*)(lds + PG8_SA(b, h) + aoff + m * 2048 + k * 1024); } while (0)
; #define PG8_LDB(dst, b, h) do { _Pragma("unroll") for (int n = 0; n < 2; ++n) _Pragma("unroll") for (int k = 0; k < 2; ++k) dst[n][k] = *(const PG8_LAS bf16x8*)(lds + PG8_SB(b, h) + boff + n * 2048 + k * 1024); } while (0)
; #define PG8_WAIT_V(n) asm volatile("s_waitcnt vmcnt(" #n ")" ::: "memory")
; #define PG8_WAIT_L(n) asm volatile("s_waitcnt lgkmcnt(" #n ")" ::: "memory")
; #define PG8_BAR __builtin_amdgcn_s_barrier()
; #define PG8_SCHED __builtin_amdgcn_sched_barrier(0)
; template <class Epi, bool ALIGN_EPI = true>
; __device__ __forceinline__ void gemm_phase(PG8_LAS unsigned char* lds, const Gemm g, const StaticOrder& S, const Epi& E) {
;     ...
;         for (int t = 0; t < nt; t += 2) {
;             const bool last = (t == nt - 2);
;             const char* a1 = cA + (size_t)(t + 1) * kstep;
;             const char* a2 = last ? nA : cA + (size_t)(t + 2) * kstep; const char* b2 = last ? nB : cB + (size_t)(t + 2) * kstep;
;             const char* a3 = a2 + kstep; const char* b3 = b2 + kstep;
;             PG8_LDB(B0, 0, 0); PG8_LDB(B1, 0, 1); PG8_SCHED; PG8_LDA(At, 0, 0); PG8_STAGE(PG8_SA(1, 1), a1 + hstepA, voffA);
;             PG8_WAIT_V(8); PG8_WAIT_L(0); PG8_BAR; PG8_MMA(0, 0, At, B0); PG8_MMA(0, 1, At, B1); PG8_BAR; PG8_SCHED;
;             PG8_LDA(At, 0, 1); PG8_STAGE(PG8_SB(0, 0), b2, voffB); PG8_STAGE(PG8_SB(0, 1), b2 + hstepB, voffB); PG8_STAGE(PG8_SA(0, 0), a2, voffA);
;             PG8_WAIT_V(8); PG8_WAIT_L(0); PG8_BAR; PG8_MMA(1, 0, At, B0); PG8_MMA(1, 1, At, B1); PG8_BAR; PG8_SCHED;
.LBB0_439:
	s_add_u32 s28, s8, 0xfffc0080
	s_addc_u32 s29, s9, -1
	s_add_i32 s53, 0, 0x10000
	s_cmp_eq_u32 s52, 12
	s_cselect_b32 s31, s3, s29
	s_cselect_b32 s30, s7, s28
	v_add_u32_e32 v32, s53, v164
	s_cselect_b32 s29, s21, s51
	s_cselect_b32 s28, s23, s50
	s_add_i32 s56, 0, 0x14000
	ds_read_b128 v[142:145], v32
	ds_read_b128 v[148:151], v32 offset:1024
	ds_read_b128 v[158:161], v32 offset:2048
	ds_read_b128 v[168:171], v32 offset:3072
	v_add_u32_e32 v32, s56, v164
	ds_read_b128 v[172:175], v32
	ds_read_b128 v[176:179], v32 offset:1024
	ds_read_b128 v[180:183], v32 offset:2048
	ds_read_b128 v[184:187], v32 offset:3072
	v_lshl_add_u64 v[146:147], s[8:9], 0, v[138:139]
	s_add_i32 m0, s41, 0xc000
	ds_read_b128 v[188:191], v166
	ds_read_b128 v[192:195], v166 offset:1024
	ds_read_b128 v[196:199], v166 offset:2048
	ds_read_b128 v[208:211], v166 offset:3072
	ds_read_b128 v[216:219], v166 offset:4096
	ds_read_b128 v[220:223], v166 offset:5120
	ds_read_b128 v[224:227], v166 offset:6144
	ds_read_b128 v[228:231], v166 offset:7168
	global_load_lds_dwordx4 v[146:147], off
	v_lshl_add_u64 v[146:147], s[8:9], 0, v[140:141]
	s_add_i32 m0, s41, 0xe000
	s_nop 0
	global_load_lds_dwordx4 v[146:147], off
	s_waitcnt vmcnt(8)
	s_waitcnt lgkmcnt(0)
	s_barrier
	s_setprio 1
	s_waitcnt lgkmcnt(0)
	v_mfma_f32_16x16x32_bf16 v[126:129], v[142:145], v[188:191], 0
	v_mfma_f32_16x16x32_bf16 v[122:125], v[158:161], v[188:191], 0
	v_mfma_f32_16x16x32_bf16 v[110:113], v[142:145], v[196:199], 0
	v_mfma_f32_16x16x32_bf16 v[106:109], v[158:161], v[196:199], 0
	v_mfma_f32_16x16x32_bf16 v[94:97], v[142:145], v[216:219], 0
	v_mfma_f32_16x16x32_bf16 v[90:93], v[158:161], v[216:219], 0
	v_mfma_f32_16x16x32_bf16 v[78:81], v[142:145], v[224:227], 0
	v_mfma_f32_16x16x32_bf16 v[74:77], v[158:161], v[224:227], 0
	v_mfma_f32_16x16x32_bf16 v[126:129], v[148:151], v[192:195], v[126:129]
	v_mfma_f32_16x16x32_bf16 v[122:125], v[168:171], v[192:195], v[122:125]
	v_mfma_f32_16x16x32_bf16 v[110:113], v[148:151], v[208:211], v[110:113]
	v_mfma_f32_16x16x32_bf16 v[106:109], v[168:171], v[208:211], v[106:109]
	v_mfma_f32_16x16x32_bf16 v[94:97], v[148:151], v[220:223], v[94:97]
	v_mfma_f32_16x16x32_bf16 v[90:93], v[168:171], v[220:223], v[90:93]
	v_mfma_f32_16x16x32_bf16 v[78:81], v[148:151], v[228:231], v[78:81]
	v_mfma_f32_16x16x32_bf16 v[74:77], v[168:171], v[228:231], v[74:77]
	v_mfma_f32_16x16x32_bf16 v[118:121], v[172:175], v[188:191], 0
	v_mfma_f32_16x16x32_bf16 v[114:117], v[180:183], v[188:191], 0
	v_mfma_f32_16x16x32_bf16 v[102:105], v[172:175], v[196:199], 0
	v_mfma_f32_16x16x32_bf16 v[98:101], v[180:183], v[196:199], 0
	v_mfma_f32_16x16x32_bf16 v[86:89], v[172:175], v[216:219], 0
	v_mfma_f32_16x16x32_bf16 v[82:85], v[180:183], v[216:219], 0
	v_mfma_f32_16x16x32_bf16 v[70:73], v[172:175], v[224:227], 0
	v_mfma_f32_16x16x32_bf16 v[66:69], v[180:183], v[224:227], 0
	v_mfma_f32_16x16x32_bf16 v[118:121], v[176:179], v[192:195], v[118:121]
	v_mfma_f32_16x16x32_bf16 v[114:117], v[184:187], v[192:195], v[114:117]
	v_mfma_f32_16x16x32_bf16 v[102:105], v[176:179], v[208:211], v[102:105]
	v_mfma_f32_16x16x32_bf16 v[98:101], v[184:187], v[208:211], v[98:101]
	v_mfma_f32_16x16x32_bf16 v[86:89], v[176:179], v[220:223], v[86:89]
	v_mfma_f32_16x16x32_bf16 v[82:85], v[184:187], v[220:223], v[82:85]
	v_mfma_f32_16x16x32_bf16 v[70:73], v[176:179], v[228:231], v[70:73]
	v_mfma_f32_16x16x32_bf16 v[66:69], v[184:187], v[228:231], v[66:69]
	s_setprio 0
	s_barrier
	s_add_i32 s53, s53, s40
	v_lshl_add_u64 v[146:147], s[28:29], 0, v[132:133]
	s_mov_b32 m0, s53
	ds_read_b128 v[188:191], v166 offset:16384
	ds_read_b128 v[192:195], v166 offset:17408
	ds_read_b128 v[196:199], v166 offset:18432
	ds_read_b128 v[208:211], v166 offset:19456
	ds_read_b128 v[216:219], v166 offset:20480
	ds_read_b128 v[220:223], v166 offset:21504
	ds_read_b128 v[224:227], v166 offset:22528
	ds_read_b128 v[228:231], v166 offset:23552
	global_load_lds_dwordx4 v[146:147], off
	s_add_i32 m0, s53, 0x2000
	s_add_u32 s58, s28, 0x40000
	v_lshl_add_u64 v[200:201], s[28:29], 0, v[136:137]
	s_addc_u32 s59, s29, 0
	s_add_i32 s53, s56, s40
	global_load_lds_dwordx4 v[200:201], off
	v_lshl_add_u64 v[204:205], s[58:59], 0, v[132:133]
	s_mov_b32 m0, s53
	v_lshl_add_u64 v[206:207], s[30:31], 0, v[134:135]
	global_load_lds_dwordx4 v[204:205], off
	v_lshl_add_u64 v[204:205], s[58:59], 0, v[136:137]
	s_add_i32 m0, s53, 0x2000
	s_nop 0
	global_load_lds_dwordx4 v[204:205], off
	v_lshl_add_u64 v[204:205], s[30:31], 0, v[130:131]
	s_mov_b32 m0, s41
	s_nop 0
	global_load_lds_dwordx4 v[204:205], off
	s_mov_b32 m0, s42
	s_nop 0
	global_load_lds_dwordx4 v[206:207], off
	s_waitcnt vmcnt(8)
	s_waitcnt lgkmcnt(0)
	s_barrier
	s_setprio 1
	s_waitcnt lgkmcnt(0)
	v_mfma_f32_16x16x32_bf16 v[62:65], v[142:145], v[188:191], 0
	v_mfma_f32_16x16x32_bf16 v[58:61], v[158:161], v[188:191], 0
	v_mfma_f32_16x16x32_bf16 v[46:49], v[142:145], v[196:199], 0
	v_mfma_f32_16x16x32_bf16 v[42:45], v[158:161], v[196:199], 0
	v_mfma_f32_16x16x32_bf16 v[28:31], v[142:145], v[216:219], 0
	v_mfma_f32_16x16x32_bf16 v[24:27], v[158:161], v[216:219], 0
	v_mfma_f32_16x16x32_bf16 v[12:15], v[142:145], v[224:227], 0
	v_mfma_f32_16x16x32_bf16 v[8:11], v[158:161], v[224:227], 0
	v_mfma_f32_16x16x32_bf16 v[62:65], v[148:151], v[192:195], v[62:65]
	v_mfma_f32_16x16x32_bf16 v[58:61], v[168:171], v[192:195], v[58:61]
	v_mfma_f32_16x16x32_bf16 v[46:49], v[148:151], v[208:211], v[46:49]
	v_mfma_f32_16x16x32_bf16 v[42:45], v[168:171], v[208:211], v[42:45]
	v_mfma_f32_16x16x32_bf16 v[28:31], v[148:151], v[220:223], v[28:31]
	v_mfma_f32_16x16x32_bf16 v[24:27], v[168:171], v[220:223], v[24:27]
	v_mfma_f32_16x16x32_bf16 v[12:15], v[148:151], v[228:231], v[12:15]
	v_mfma_f32_16x16x32_bf16 v[8:11], v[168:171], v[228:231], v[8:11]
	v_mfma_f32_16x16x32_bf16 v[54:57], v[172:175], v[188:191], 0
	v_mfma_f32_16x16x32_bf16 v[50:53], v[180:183], v[188:191], 0
	v_mfma_f32_16x16x32_bf16 v[38:41], v[172:175], v[196:199], 0
	v_mfma_f32_16x16x32_bf16 v[34:37], v[180:183], v[196:199], 0
	v_mfma_f32_16x16x32_bf16 v[20:23], v[172:175], v[216:219], 0
	v_mfma_f32_16x16x32_bf16 v[16:19], v[180:183], v[216:219], 0
	v_mfma_f32_16x16x32_bf16 v[4:7], v[172:175], v[224:227], 0
	v_mfma_f32_16x16x32_bf16 v[0:3], v[180:183], v[224:227], 0
	v_mfma_f32_16x16x32_bf16 v[54:57], v[176:179], v[192:195], v[54:57]
	v_mfma_f32_16x16x32_bf16 v[50:53], v[184:187], v[192:195], v[50:53]
	v_mfma_f32_16x16x32_bf16 v[38:41], v[176:179], v[208:211], v[38:41]
	v_mfma_f32_16x16x32_bf16 v[34:37], v[184:187], v[208:211], v[34:37]
	v_mfma_f32_16x16x32_bf16 v[20:23], v[176:179], v[220:223], v[20:23]
	v_mfma_f32_16x16x32_bf16 v[16:19], v[184:187], v[220:223], v[16:19]
	v_mfma_f32_16x16x32_bf16 v[4:7], v[176:179], v[228:231], v[4:7]
	v_mfma_f32_16x16x32_bf16 v[0:3], v[184:187], v[228:231], v[0:3]
	s_setprio 0
	s_barrier
	s_branch .Lp3_439

; #define PG8_STAGE(bufoff, gbase, voff) do { _Pragma("unroll") for (int _i = 0; _i < 2; ++_i) \
;         __builtin_amdgcn_global_load_lds((const unsigned*)((const char*)(gbase) + (voff)[_i]), (PG8_LAS unsigned*)(lds + (bufoff) + ldsw + _i * 8192), 16, 0, 0); } while (0)
; #define PG8_LDA(dst, b, h) do { _Pragma("unroll") for (int m = 0; m < 4; ++m) _Pragma("unroll") for (int k = 0; k < 2; ++k) dst[m][k] = *(const PG8_LAS bf16x8*)(lds + PG8_SA(b, h) + aoff + m * 2048 + k * 1024); } while (0)
; #define PG8_LDB(dst, b, h) do { _Pragma("unroll") for (int n = 0; n < 2; ++n) _Pragma("unroll") for (int k = 0; k < 2; ++k) dst[n][k] = *(const PG8_LAS bf16x8*)(lds + PG8_SB(b, h) + boff + n * 2048 + k * 1024); } while (0)
; #define PG8_WAIT_V(n) asm volatile("s_waitcnt vmcnt(" #n ")" ::: "memory")
; #define PG8_WAIT_L(n) asm volatile("s_waitcnt lgkmcnt(" #n ")" ::: "memory")
; #define PG8_BAR __builtin_amdgcn_s_barrier()
; #define PG8_SCHED __builtin_amdgcn_sched_barrier(0)
; template <class Epi, bool ALIGN_EPI = true>
; __device__ __forceinline__ void gemm_phase(PG8_LAS unsigned char* lds, const Gemm g, const StaticOrder& S, const Epi& E) {
;     ...
;             PG8_LDB(B0, 1, 0); PG8_LDB(B1, 1, 1); PG8_SCHED; PG8_LDA(At, 1, 0); PG8_STAGE(PG8_SA(0, 1), a2 + hstepA, voffA);
;             PG8_WAIT_V(8); PG8_WAIT_L(0); PG8_BAR; PG8_MMA(0, 0, At, B0); PG8_MMA(0, 1, At, B1); PG8_BAR; PG8_SCHED;
.Lp3_439:
	s_add_i32 s53, 0, 0x18000
	v_add_u32_e32 v32, s53, v164
	s_add_i32 s56, 0, 0x1c000
	ds_read_b128 v[142:145], v32
	ds_read_b128 v[148:151], v32 offset:1024
	ds_read_b128 v[158:161], v32 offset:2048
	ds_read_b128 v[168:171], v32 offset:3072
	v_add_u32_e32 v32, s56, v164
	ds_read_b128 v[172:175], v32
	ds_read_b128 v[176:179], v32 offset:1024
	ds_read_b128 v[180:183], v32 offset:2048
	ds_read_b128 v[184:187], v32 offset:3072
	s_add_u32 s30, s30, 0x40000
	s_addc_u32 s31, s31, 0
	s_mov_b32 m0, s43
	v_lshl_add_u64 v[232:233], s[30:31], 0, v[130:131]
	ds_read_b128 v[188:191], v166 offset:32768
	ds_read_b128 v[192:195], v166 offset:33792
	ds_read_b128 v[196:199], v166 offset:34816
	ds_read_b128 v[208:211], v166 offset:35840
	ds_read_b128 v[216:219], v166 offset:36864
	ds_read_b128 v[220:223], v166 offset:37888
	ds_read_b128 v[224:227], v166 offset:38912
	ds_read_b128 v[228:231], v166 offset:39936
	global_load_lds_dwordx4 v[232:233], off
	v_lshl_add_u64 v[232:233], s[30:31], 0, v[134:135]
	s_mov_b32 m0, s44
	s_nop 0
	global_load_lds_dwordx4 v[232:233], off
	s_waitcnt vmcnt(8)
	s_waitcnt lgkmcnt(0)
	s_barrier
	s_setprio 1
	s_waitcnt lgkmcnt(0)
	v_mfma_f32_16x16x32_bf16 v[126:129], v[142:145], v[188:191], v[126:129]
	v_mfma_f32_16x16x32_bf16 v[122:125], v[158:161], v[188:191], v[122:125]
	v_mfma_f32_16x16x32_bf16 v[110:113], v[142:145], v[196:199], v[110:113]
	v_mfma_f32_16x16x32_bf16 v[106:109], v[158:161], v[196:199], v[106:109]
	v_mfma_f32_16x16x32_bf16 v[94:97], v[142:145], v[216:219], v[94:97]
	v_mfma_f32_16x16x32_bf16 v[90:93], v[158:161], v[216:219], v[90:93]
	v_mfma_f32_16x16x32_bf16 v[78:81], v[142:145], v[224:227], v[78:81]
	v_mfma_f32_16x16x32_bf16 v[74:77], v[158:161], v[224:227], v[74:77]
	v_mfma_f32_16x16x32_bf16 v[126:129], v[148:151], v[192:195], v[126:129]
	v_mfma_f32_16x16x32_bf16 v[122:125], v[168:171], v[192:195], v[122:125]
	v_mfma_f32_16x16x32_bf16 v[110:113], v[148:151], v[208:211], v[110:113]
	v_mfma_f32_16x16x32_bf16 v[106:109], v[168:171], v[208:211], v[106:109]
	v_mfma_f32_16x16x32_bf16 v[94:97], v[148:151], v[220:223], v[94:97]
	v_mfma_f32_16x16x32_bf16 v[90:93], v[168:171], v[220:223], v[90:93]
	v_mfma_f32_16x16x32_bf16 v[78:81], v[148:151], v[228:231], v[78:81]
	v_mfma_f32_16x16x32_bf16 v[74:77], v[168:171], v[228:231], v[74:77]
	v_mfma_f32_16x16x32_bf16 v[118:121], v[172:175], v[188:191], v[118:121]
	v_mfma_f32_16x16x32_bf16 v[114:117], v[180:183], v[188:191], v[114:117]
	v_mfma_f32_16x16x32_bf16 v[102:105], v[172:175], v[196:199], v[102:105]
	v_mfma_f32_16x16x32_bf16 v[98:101], v[180:183], v[196:199], v[98:101]
	v_mfma_f32_16x16x32_bf16 v[86:89], v[172:175], v[216:219], v[86:89]
	v_mfma_f32_16x16x32_bf16 v[82:85], v[180:183], v[216:219], v[82:85]
	v_mfma_f32_16x16x32_bf16 v[70:73], v[172:175], v[224:227], v[70:73]
	v_mfma_f32_16x16x32_bf16 v[66:69], v[180:183], v[224:227], v[66:69]
	v_mfma_f32_16x16x32_bf16 v[118:121], v[176:179], v[192:195], v[118:121]
	v_mfma_f32_16x16x32_bf16 v[114:117], v[184:187], v[192:195], v[114:117]
	v_mfma_f32_16x16x32_bf16 v[102:105], v[176:179], v[208:211], v[102:105]
	v_mfma_f32_16x16x32_bf16 v[98:101], v[184:187], v[208:211], v[98:101]
	v_mfma_f32_16x16x32_bf16 v[86:89], v[176:179], v[220:223], v[86:89]
	v_mfma_f32_16x16x32_bf16 v[82:85], v[184:187], v[220:223], v[82:85]
	v_mfma_f32_16x16x32_bf16 v[70:73], v[176:179], v[228:231], v[70:73]
	v_mfma_f32_16x16x32_bf16 v[66:69], v[184:187], v[228:231], v[66:69]
	s_setprio 0
	s_barrier
; #define PG8_STAGE(bufoff, gbase, voff) do { _Pragma("unroll") for (int _i = 0; _i < 2; ++_i) \
;         __builtin_amdgcn_global_load_lds((const unsigned*)((const char*)(gbase) + (voff)[_i]), (PG8_LAS unsigned*)(lds + (bufoff) + ldsw + _i * 8192), 16, 0, 0); } while (0)
; #define PG8_LDA(dst, b, h) do { _Pragma("unroll") for (int m = 0; m < 4; ++m) _Pragma("unroll") for (int k = 0; k < 2; ++k) dst[m][k] = *(const PG8_LAS bf16x8*)(lds + PG8_SA(b, h) + aoff + m * 2048 + k * 1024); } while (0)
; #define PG8_LDB(dst, b, h) do { _Pragma("unroll") for (int n = 0; n < 2; ++n) _Pragma("unroll") for (int k = 0; k < 2; ++k) dst[n][k] = *(const PG8_LAS bf16x8*)(lds + PG8_SB(b, h) + boff + n * 2048 + k * 1024); } while (0)
; #define PG8_BAR __builtin_amdgcn_s_barrier()
; template <class Epi, bool ALIGN_EPI = true>
; __device__ __forceinline__ void gemm_phase(PG8_LAS unsigned char* lds, const Gemm g, const StaticOrder& S, const Epi& E) {
;     ...
;         for (int t = 0; t < nt; t += 2) {
;             const bool last = (t == nt - 2);
;             const char* a1 = cA + (size_t)(t + 1) * kstep;
;             const char* a2 = last ? nA : cA + (size_t)(t + 2) * kstep; const char* b2 = last ? nB : cB + (size_t)(t + 2) * kstep;
;             const char* a3 = a2 + kstep; const char* b3 = b2 + kstep;
;             PG8_LDB(B0, 0, 0); PG8_LDB(B1, 0, 1); PG8_SCHED; PG8_LDA(At, 0, 0); PG8_STAGE(PG8_SA(1, 1), a1 + hstepA, voffA);
;             PG8_WAIT_V(8); PG8_WAIT_L(0); PG8_BAR; PG8_MMA(0, 0, At, B0); PG8_MMA(0, 1, At, B1); PG8_BAR; PG8_SCHED;
;             PG8_LDA(At, 0, 1); PG8_STAGE(PG8_SB(0, 0), b2, voffB); PG8_STAGE(PG8_SB(0, 1), b2 + hstepB, voffB); PG8_STAGE(PG8_SA(0, 0), a2, voffA);
;             PG8_WAIT_V(8); PG8_WAIT_L(0); PG8_BAR; PG8_MMA(1, 0, At, B0); PG8_MMA(1, 1, At, B1); PG8_BAR; PG8_SCHED;
;             PG8_LDB(B0, 1, 0); PG8_LDB(B1, 1, 1); PG8_SCHED; PG8_LDA(At, 1, 0); PG8_STAGE(PG8_SA(0, 1), a2 + hstepA, voffA);
;             PG8_WAIT_V(8); PG8_WAIT_L(0); PG8_BAR; PG8_MMA(0, 0, At, B0); PG8_MMA(0, 1, At, B1); PG8_BAR; PG8_SCHED;
;             PG8_LDA(At, 1, 1); PG8_STAGE(PG8_SB(1, 0), b3, voffB); PG8_STAGE(PG8_SB(1, 1), b3 + hstepB, voffB); PG8_STAGE(PG8_SA(1, 0), a3, voffA);
;             PG8_WAIT_V(8); PG8_WAIT_L(0); PG8_BAR; PG8_MMA(1, 0, At, B0); PG8_MMA(1, 1, At, B1); PG8_BAR; PG8_SCHED;
;         }
;         if constexpr (ALIGN_EPI) { if (wr == 0) PG8_BAR; }
	s_add_i32 s30, s53, s40
	v_lshl_add_u64 v[146:147], v[146:147], 0, s[60:61]
	s_mov_b32 m0, s30
	ds_read_b128 v[188:191], v166 offset:49152
	ds_read_b128 v[192:195], v166 offset:50176
	ds_read_b128 v[196:199], v166 offset:51200
	ds_read_b128 v[208:211], v166 offset:52224
	ds_read_b128 v[216:219], v166 offset:53248
	ds_read_b128 v[220:223], v166 offset:54272
	ds_read_b128 v[224:227], v166 offset:55296
	ds_read_b128 v[228:231], v166 offset:56320
	global_load_lds_dwordx4 v[146:147], off
	s_add_i32 m0, s30, 0x2000
	s_add_u32 s28, s28, 0x40080
	v_lshl_add_u64 v[146:147], v[200:201], 0, s[60:61]
	s_addc_u32 s29, s29, 0
	s_add_i32 s30, s56, s40
	global_load_lds_dwordx4 v[146:147], off
	v_lshl_add_u64 v[146:147], s[28:29], 0, v[132:133]
	s_mov_b32 m0, s30
	s_nop 0
	global_load_lds_dwordx4 v[146:147], off
	v_lshl_add_u64 v[146:147], s[28:29], 0, v[136:137]
	s_add_i32 m0, s30, 0x2000
	s_nop 0
	global_load_lds_dwordx4 v[146:147], off
	v_lshl_add_u64 v[146:147], v[204:205], 0, s[60:61]
	s_mov_b32 m0, s45
	s_nop 0
	global_load_lds_dwordx4 v[146:147], off
	v_lshl_add_u64 v[146:147], v[206:207], 0, s[60:61]
	s_mov_b32 m0, s46
	s_nop 0
	global_load_lds_dwordx4 v[146:147], off
	s_add_i32 s52, s52, 2
	s_add_u32 s8, s8, 0x100
	s_addc_u32 s9, s9, 0
	s_add_u32 s50, s50, 0x100
	s_addc_u32 s51, s51, 0
	s_add_u32 s28, s8, 0xfffc0080
	s_addc_u32 s29, s9, -1
	s_add_i32 s53, 0, 0x10000
	s_cmp_eq_u32 s52, 12
	s_cselect_b32 s31, s3, s29
	s_cselect_b32 s30, s7, s28
	v_add_u32_e32 v32, s53, v164
	s_cselect_b32 s29, s21, s51
	s_cselect_b32 s28, s23, s50
	s_add_i32 s56, 0, 0x14000
	s_cmp_gt_u32 s52, 13
	s_waitcnt vmcnt(8)
	s_waitcnt lgkmcnt(0)
	s_barrier
	s_setprio 1
	s_waitcnt lgkmcnt(0)
	v_mfma_f32_16x16x32_bf16 v[62:65], v[142:145], v[188:191], v[62:65]
	v_mfma_f32_16x16x32_bf16 v[58:61], v[158:161], v[188:191], v[58:61]
	v_mfma_f32_16x16x32_bf16 v[46:49], v[142:145], v[196:199], v[46:49]
	v_mfma_f32_16x16x32_bf16 v[42:45], v[158:161], v[196:199], v[42:45]
	v_mfma_f32_16x16x32_bf16 v[28:31], v[142:145], v[216:219], v[28:31]
	v_mfma_f32_16x16x32_bf16 v[24:27], v[158:161], v[216:219], v[24:27]
	v_mfma_f32_16x16x32_bf16 v[12:15], v[142:145], v[224:227], v[12:15]
	v_mfma_f32_16x16x32_bf16 v[8:11], v[158:161], v[224:227], v[8:11]
	v_mfma_f32_16x16x32_bf16 v[62:65], v[148:151], v[192:195], v[62:65]
	v_mfma_f32_16x16x32_bf16 v[58:61], v[168:171], v[192:195], v[58:61]
	v_mfma_f32_16x16x32_bf16 v[46:49], v[148:151], v[208:211], v[46:49]
	v_mfma_f32_16x16x32_bf16 v[42:45], v[168:171], v[208:211], v[42:45]
	v_mfma_f32_16x16x32_bf16 v[28:31], v[148:151], v[220:223], v[28:31]
	v_mfma_f32_16x16x32_bf16 v[24:27], v[168:171], v[220:223], v[24:27]
	v_mfma_f32_16x16x32_bf16 v[12:15], v[148:151], v[228:231], v[12:15]
	v_mfma_f32_16x16x32_bf16 v[8:11], v[168:171], v[228:231], v[8:11]
	v_mfma_f32_16x16x32_bf16 v[54:57], v[172:175], v[188:191], v[54:57]
	v_mfma_f32_16x16x32_bf16 v[50:53], v[180:183], v[188:191], v[50:53]
	v_mfma_f32_16x16x32_bf16 v[38:41], v[172:175], v[196:199], v[38:41]
	v_mfma_f32_16x16x32_bf16 v[34:37], v[180:183], v[196:199], v[34:37]
	v_mfma_f32_16x16x32_bf16 v[20:23], v[172:175], v[216:219], v[20:23]
	v_mfma_f32_16x16x32_bf16 v[16:19], v[180:183], v[216:219], v[16:19]
	v_mfma_f32_16x16x32_bf16 v[4:7], v[172:175], v[224:227], v[4:7]
	v_mfma_f32_16x16x32_bf16 v[0:3], v[180:183], v[224:227], v[0:3]
	v_mfma_f32_16x16x32_bf16 v[54:57], v[176:179], v[192:195], v[54:57]
	v_mfma_f32_16x16x32_bf16 v[50:53], v[184:187], v[192:195], v[50:53]
	v_mfma_f32_16x16x32_bf16 v[38:41], v[176:179], v[208:211], v[38:41]
	v_mfma_f32_16x16x32_bf16 v[34:37], v[184:187], v[208:211], v[34:37]
	v_mfma_f32_16x16x32_bf16 v[20:23], v[176:179], v[220:223], v[20:23]
	v_mfma_f32_16x16x32_bf16 v[16:19], v[184:187], v[220:223], v[16:19]
	v_mfma_f32_16x16x32_bf16 v[4:7], v[176:179], v[228:231], v[4:7]
	v_mfma_f32_16x16x32_bf16 v[0:3], v[184:187], v[228:231], v[0:3]
	s_setprio 0
	s_barrier
	s_cbranch_scc0 .Lrot_439
	s_and_b64 vcc, exec, s[18:19]
	s_cbranch_vccz .LBB0_442
	s_barrier

; template <class Epi, bool ALIGN_EPI = true>
; __device__ __forceinline__ void gemm_phase(PG8_LAS unsigned char* lds, const Gemm g, const StaticOrder& S, const Epi& E) {
;     ...
;         const bool has_next = S.next(ui + 1, nxt);
;         const char* nA = has_next ? (const char*)g.A + (size_t)nxt.pm * tstepA + (size_t)nxt.ks * ksA : cA; const char* nB = has_next ? (const char*)g.Bt + (size_t)nxt.pn * tstepB + (size_t)nxt.ks * ksA : cB;
;         for (int t = 0; t < nt; t += 2) {
;             const bool last = (t == nt - 2);
;             const char* a1 = cA + (size_t)(t + 1) * kstep;
;             const char* a2 = last ? nA : cA + (size_t)(t + 2) * kstep; const char* b2 = last ? nB : cB + (size_t)(t + 2) * kstep;
;             const char* a3 = a2 + kstep; const char* b3 = b2 + kstep;
.LBB0_794:
	s_ashr_i32 s37, s36, 31
	s_lshl_b64 s[6:7], s[36:37], 19
	s_add_u32 s9, s52, s6
	s_addc_u32 s35, s53, s7
	s_and_b64 s[6:7], s[4:5], exec
	s_cselect_b32 s39, s35, s47
	s_cselect_b32 s38, s9, s46
	s_ashr_i32 s35, s34, 31
	s_lshl_b64 s[6:7], s[34:35], 19
	s_add_u32 s9, s56, s6
	s_addc_u32 s35, s58, s7
	s_and_b64 s[6:7], s[4:5], exec
	s_cselect_b32 s41, s35, s45
	s_cselect_b32 s40, s9, s44
	s_add_u32 s6, s46, 0x40080
	s_addc_u32 s7, s47, 0
	s_add_u32 s9, s44, 0x100
	s_addc_u32 s35, s45, 0
	s_mov_b32 s37, -2
; #define PG8_STAGE(bufoff, gbase, voff) do { _Pragma("unroll") for (int _i = 0; _i < 2; ++_i) \
;         __builtin_amdgcn_global_load_lds((const unsigned*)((const char*)(gbase) + (voff)[_i]), (PG8_LAS unsigned*)(lds + (bufoff) + ldsw + _i * 8192), 16, 0, 0); } while (0)
; #define PG8_LDA(dst, b, h) do { _Pragma("unroll") for (int m = 0; m < 4; ++m) _Pragma("unroll") for (int k = 0; k < 2; ++k) dst[m][k] = *(const PG8_LAS bf16x8*)(lds + PG8_SA(b, h) + aoff + m * 2048 + k * 1024); } while (0)
; #define PG8_LDB(dst, b, h) do { _Pragma("unroll") for (int n = 0; n < 2; ++n) _Pragma("unroll") for (int k = 0; k < 2; ++k) dst[n][k] = *(const PG8_LAS bf16x8*)(lds + PG8_SB(b, h) + boff + n * 2048 + k * 1024); } while (0)
; #define PG8_WAIT_V(n) asm volatile("s_waitcnt vmcnt(" #n ")" ::: "memory")
; #define PG8_WAIT_L(n) asm volatile("s_waitcnt lgkmcnt(" #n ")" ::: "memory")
; #define PG8_BAR __builtin_amdgcn_s_barrier()
; #define PG8_SCHED __builtin_amdgcn_sched_barrier(0)
; template <class Epi, bool ALIGN_EPI = true>
; __device__ __forceinline__ void gemm_phase(PG8_LAS unsigned char* lds, const Gemm g, const StaticOrder& S, const Epi& E) {
;     ...
;         for (int t = 0; t < nt; t += 2) {
;             const bool last = (t == nt - 2);
;             const char* a1 = cA + (size_t)(t + 1) * kstep;
;             const char* a2 = last ? nA : cA + (size_t)(t + 2) * kstep; const char* b2 = last ? nB : cB + (size_t)(t + 2) * kstep;
;             const char* a3 = a2 + kstep; const char* b3 = b2 + kstep;
;             PG8_LDB(B0, 0, 0); PG8_LDB(B1, 0, 1); PG8_SCHED; PG8_LDA(At, 0, 0); PG8_STAGE(PG8_SA(1, 1), a1 + hstepA, voffA);
;             PG8_WAIT_V(8); PG8_WAIT_L(0); PG8_BAR; PG8_MMA(0, 0, At, B0); PG8_MMA(0, 1, At, B1); PG8_BAR; PG8_SCHED;
;             PG8_LDA(At, 0, 1); PG8_STAGE(PG8_SB(0, 0), b2, voffB); PG8_STAGE(PG8_SB(0, 1), b2 + hstepB, voffB); PG8_STAGE(PG8_SA(0, 0), a2, voffA);
;             PG8_WAIT_V(8); PG8_WAIT_L(0); PG8_BAR; PG8_MMA(1, 0, At, B0); PG8_MMA(1, 1, At, B1); PG8_BAR; PG8_SCHED;
.LBB0_795:
	s_add_u32 s43, s6, 0xfffc0080
	s_addc_u32 s44, s7, -1
	s_add_i32 s75, 0, 0x10000
	s_cmp_eq_u32 s37, 12
	s_cselect_b32 s47, s39, s44
	s_cselect_b32 s46, s38, s43
	v_add_u32_e32 v32, s75, v165
	s_cselect_b32 s45, s41, s35
	s_cselect_b32 s44, s40, s9
	s_add_i32 s43, 0, 0x14000
	ds_read_b128 v[142:145], v32
	ds_read_b128 v[148:151], v32 offset:1024
	ds_read_b128 v[158:161], v32 offset:2048
	ds_read_b128 v[168:171], v32 offset:3072
	v_add_u32_e32 v32, s43, v165
	ds_read_b128 v[172:175], v32
	ds_read_b128 v[176:179], v32 offset:1024
	ds_read_b128 v[180:183], v32 offset:2048
	ds_read_b128 v[184:187], v32 offset:3072
	v_lshl_add_u64 v[146:147], s[6:7], 0, v[138:139]
	s_add_i32 m0, s59, 0xc000
	ds_read_b128 v[188:191], v167
	ds_read_b128 v[192:195], v167 offset:1024
	ds_read_b128 v[196:199], v167 offset:2048
	ds_read_b128 v[208:211], v167 offset:3072
	ds_read_b128 v[216:219], v167 offset:4096
	ds_read_b128 v[220:223], v167 offset:5120
	ds_read_b128 v[224:227], v167 offset:6144
	ds_read_b128 v[228:231], v167 offset:7168
	global_load_lds_dwordx4 v[146:147], off
	v_lshl_add_u64 v[146:147], s[6:7], 0, v[140:141]
	s_add_i32 m0, s59, 0xe000
	s_nop 0
	global_load_lds_dwordx4 v[146:147], off
	s_waitcnt vmcnt(8)
	s_waitcnt lgkmcnt(0)
	s_barrier
	s_setprio 1
	s_waitcnt lgkmcnt(0)
	v_mfma_f32_16x16x32_bf16 v[126:129], v[142:145], v[188:191], 0
	v_mfma_f32_16x16x32_bf16 v[122:125], v[158:161], v[188:191], 0
	v_mfma_f32_16x16x32_bf16 v[110:113], v[142:145], v[196:199], 0
	v_mfma_f32_16x16x32_bf16 v[106:109], v[158:161], v[196:199], 0
	v_mfma_f32_16x16x32_bf16 v[94:97], v[142:145], v[216:219], 0
	v_mfma_f32_16x16x32_bf16 v[90:93], v[158:161], v[216:219], 0
	v_mfma_f32_16x16x32_bf16 v[78:81], v[142:145], v[224:227], 0
	v_mfma_f32_16x16x32_bf16 v[74:77], v[158:161], v[224:227], 0
	v_mfma_f32_16x16x32_bf16 v[126:129], v[148:151], v[192:195], v[126:129]
	v_mfma_f32_16x16x32_bf16 v[122:125], v[168:171], v[192:195], v[122:125]
	v_mfma_f32_16x16x32_bf16 v[110:113], v[148:151], v[208:211], v[110:113]
	v_mfma_f32_16x16x32_bf16 v[106:109], v[168:171], v[208:211], v[106:109]
	v_mfma_f32_16x16x32_bf16 v[94:97], v[148:151], v[220:223], v[94:97]
	v_mfma_f32_16x16x32_bf16 v[90:93], v[168:171], v[220:223], v[90:93]
	v_mfma_f32_16x16x32_bf16 v[78:81], v[148:151], v[228:231], v[78:81]
	v_mfma_f32_16x16x32_bf16 v[74:77], v[168:171], v[228:231], v[74:77]
	v_mfma_f32_16x16x32_bf16 v[118:121], v[172:175], v[188:191], 0
	v_mfma_f32_16x16x32_bf16 v[114:117], v[180:183], v[188:191], 0
	v_mfma_f32_16x16x32_bf16 v[102:105], v[172:175], v[196:199], 0
	v_mfma_f32_16x16x32_bf16 v[98:101], v[180:183], v[196:199], 0
	v_mfma_f32_16x16x32_bf16 v[86:89], v[172:175], v[216:219], 0
	v_mfma_f32_16x16x32_bf16 v[82:85], v[180:183], v[216:219], 0
	v_mfma_f32_16x16x32_bf16 v[70:73], v[172:175], v[224:227], 0
	v_mfma_f32_16x16x32_bf16 v[66:69], v[180:183], v[224:227], 0
	v_mfma_f32_16x16x32_bf16 v[118:121], v[176:179], v[192:195], v[118:121]
	v_mfma_f32_16x16x32_bf16 v[114:117], v[184:187], v[192:195], v[114:117]
	v_mfma_f32_16x16x32_bf16 v[102:105], v[176:179], v[208:211], v[102:105]
	v_mfma_f32_16x16x32_bf16 v[98:101], v[184:187], v[208:211], v[98:101]
	v_mfma_f32_16x16x32_bf16 v[86:89], v[176:179], v[220:223], v[86:89]
	v_mfma_f32_16x16x32_bf16 v[82:85], v[184:187], v[220:223], v[82:85]
	v_mfma_f32_16x16x32_bf16 v[70:73], v[176:179], v[228:231], v[70:73]
	v_mfma_f32_16x16x32_bf16 v[66:69], v[184:187], v[228:231], v[66:69]
	s_setprio 0
	s_barrier
	s_add_i32 s75, s75, s51
	v_lshl_add_u64 v[146:147], s[44:45], 0, v[132:133]
	s_mov_b32 m0, s75
	ds_read_b128 v[188:191], v167 offset:16384
	ds_read_b128 v[192:195], v167 offset:17408
	ds_read_b128 v[196:199], v167 offset:18432
	ds_read_b128 v[208:211], v167 offset:19456
	ds_read_b128 v[216:219], v167 offset:20480
	ds_read_b128 v[220:223], v167 offset:21504
	ds_read_b128 v[224:227], v167 offset:22528
	ds_read_b128 v[228:231], v167 offset:23552
	global_load_lds_dwordx4 v[146:147], off
	s_add_i32 m0, s75, 0x2000
	s_add_u32 s76, s44, 0x40000
	v_lshl_add_u64 v[162:163], s[44:45], 0, v[136:137]
	s_addc_u32 s77, s45, 0
	s_add_i32 s43, s43, s51
	global_load_lds_dwordx4 v[162:163], off
	v_lshl_add_u64 v[200:201], s[76:77], 0, v[132:133]
	s_mov_b32 m0, s43
	v_lshl_add_u64 v[204:205], s[46:47], 0, v[134:135]
	global_load_lds_dwordx4 v[200:201], off
	v_lshl_add_u64 v[200:201], s[76:77], 0, v[136:137]
	s_add_i32 m0, s43, 0x2000
	s_nop 0
	global_load_lds_dwordx4 v[200:201], off
	v_lshl_add_u64 v[200:201], s[46:47], 0, v[130:131]
	s_mov_b32 m0, s59
	s_nop 0
	global_load_lds_dwordx4 v[200:201], off
	s_mov_b32 m0, s62
	s_nop 0
	global_load_lds_dwordx4 v[204:205], off
	s_waitcnt vmcnt(8)
	s_waitcnt lgkmcnt(0)
	s_barrier
	s_setprio 1
	s_waitcnt lgkmcnt(0)
	v_mfma_f32_16x16x32_bf16 v[62:65], v[142:145], v[188:191], 0
	v_mfma_f32_16x16x32_bf16 v[58:61], v[158:161], v[188:191], 0
	v_mfma_f32_16x16x32_bf16 v[46:49], v[142:145], v[196:199], 0
	v_mfma_f32_16x16x32_bf16 v[42:45], v[158:161], v[196:199], 0
	v_mfma_f32_16x16x32_bf16 v[28:31], v[142:145], v[216:219], 0
	v_mfma_f32_16x16x32_bf16 v[24:27], v[158:161], v[216:219], 0
	v_mfma_f32_16x16x32_bf16 v[12:15], v[142:145], v[224:227], 0
	v_mfma_f32_16x16x32_bf16 v[8:11], v[158:161], v[224:227], 0
	v_mfma_f32_16x16x32_bf16 v[62:65], v[148:151], v[192:195], v[62:65]
	v_mfma_f32_16x16x32_bf16 v[58:61], v[168:171], v[192:195], v[58:61]
	v_mfma_f32_16x16x32_bf16 v[46:49], v[148:151], v[208:211], v[46:49]
	v_mfma_f32_16x16x32_bf16 v[42:45], v[168:171], v[208:211], v[42:45]
	v_mfma_f32_16x16x32_bf16 v[28:31], v[148:151], v[220:223], v[28:31]
	v_mfma_f32_16x16x32_bf16 v[24:27], v[168:171], v[220:223], v[24:27]
	v_mfma_f32_16x16x32_bf16 v[12:15], v[148:151], v[228:231], v[12:15]
	v_mfma_f32_16x16x32_bf16 v[8:11], v[168:171], v[228:231], v[8:11]
	v_mfma_f32_16x16x32_bf16 v[54:57], v[172:175], v[188:191], 0
	v_mfma_f32_16x16x32_bf16 v[50:53], v[180:183], v[188:191], 0
	v_mfma_f32_16x16x32_bf16 v[38:41], v[172:175], v[196:199], 0
	v_mfma_f32_16x16x32_bf16 v[34:37], v[180:183], v[196:199], 0
	v_mfma_f32_16x16x32_bf16 v[20:23], v[172:175], v[216:219], 0
	v_mfma_f32_16x16x32_bf16 v[16:19], v[180:183], v[216:219], 0
	v_mfma_f32_16x16x32_bf16 v[4:7], v[172:175], v[224:227], 0
	v_mfma_f32_16x16x32_bf16 v[0:3], v[180:183], v[224:227], 0
	v_mfma_f32_16x16x32_bf16 v[54:57], v[176:179], v[192:195], v[54:57]
	v_mfma_f32_16x16x32_bf16 v[50:53], v[184:187], v[192:195], v[50:53]
	v_mfma_f32_16x16x32_bf16 v[38:41], v[176:179], v[208:211], v[38:41]
	v_mfma_f32_16x16x32_bf16 v[34:37], v[184:187], v[208:211], v[34:37]
	v_mfma_f32_16x16x32_bf16 v[20:23], v[176:179], v[220:223], v[20:23]
	v_mfma_f32_16x16x32_bf16 v[16:19], v[184:187], v[220:223], v[16:19]
	v_mfma_f32_16x16x32_bf16 v[4:7], v[176:179], v[228:231], v[4:7]
	v_mfma_f32_16x16x32_bf16 v[0:3], v[184:187], v[228:231], v[0:3]
	s_setprio 0
	s_barrier
	s_branch .Lp3_795

; #define PG8_STAGE(bufoff, gbase, voff) do { _Pragma("unroll") for (int _i = 0; _i < 2; ++_i) \
;         __builtin_amdgcn_global_load_lds((const unsigned*)((const char*)(gbase) + (voff)[_i]), (PG8_LAS unsigned*)(lds + (bufoff) + ldsw + _i * 8192), 16, 0, 0); } while (0)
; #define PG8_LDA(dst, b, h) do { _Pragma("unroll") for (int m = 0; m < 4; ++m) _Pragma("unroll") for (int k = 0; k < 2; ++k) dst[m][k] = *(const PG8_LAS bf16x8*)(lds + PG8_SA(b, h) + aoff + m * 2048 + k * 1024); } while (0)
; #define PG8_LDB(dst, b, h) do { _Pragma("unroll") for (int n = 0; n < 2; ++n) _Pragma("unroll") for (int k = 0; k < 2; ++k) dst[n][k] = *(const PG8_LAS bf16x8*)(lds + PG8_SB(b, h) + boff + n * 2048 + k * 1024); } while (0)
; #define PG8_WAIT_V(n) asm volatile("s_waitcnt vmcnt(" #n ")" ::: "memory")
; #define PG8_WAIT_L(n) asm volatile("s_waitcnt lgkmcnt(" #n ")" ::: "memory")
; #define PG8_BAR __builtin_amdgcn_s_barrier()
; #define PG8_SCHED __builtin_amdgcn_sched_barrier(0)
; template <class Epi, bool ALIGN_EPI = true>
; __device__ __forceinline__ void gemm_phase(PG8_LAS unsigned char* lds, const Gemm g, const StaticOrder& S, const Epi& E) {
;     ...
;             PG8_LDB(B0, 1, 0); PG8_LDB(B1, 1, 1); PG8_SCHED; PG8_LDA(At, 1, 0); PG8_STAGE(PG8_SA(0, 1), a2 + hstepA, voffA);
;             PG8_WAIT_V(8); PG8_WAIT_L(0); PG8_BAR; PG8_MMA(0, 0, At, B0); PG8_MMA(0, 1, At, B1); PG8_BAR; PG8_SCHED;
.Lp3_795:
	s_add_i32 s43, 0, 0x18000
	v_add_u32_e32 v32, s43, v165
	s_add_i32 s75, 0, 0x1c000
	ds_read_b128 v[142:145], v32
	ds_read_b128 v[148:151], v32 offset:1024
	ds_read_b128 v[158:161], v32 offset:2048
	ds_read_b128 v[168:171], v32 offset:3072
	v_add_u32_e32 v32, s75, v165
	ds_read_b128 v[172:175], v32
	ds_read_b128 v[176:179], v32 offset:1024
	ds_read_b128 v[180:183], v32 offset:2048
	ds_read_b128 v[184:187], v32 offset:3072
	s_add_u32 s46, s46, 0x40000
	s_addc_u32 s47, s47, 0
	s_mov_b32 m0, s63
	v_lshl_add_u64 v[206:207], s[46:47], 0, v[130:131]
	ds_read_b128 v[188:191], v167 offset:32768
	ds_read_b128 v[192:195], v167 offset:33792
	ds_read_b128 v[196:199], v167 offset:34816
	ds_read_b128 v[208:211], v167 offset:35840
	ds_read_b128 v[216:219], v167 offset:36864
	ds_read_b128 v[220:223], v167 offset:37888
	ds_read_b128 v[224:227], v167 offset:38912
	ds_read_b128 v[228:231], v167 offset:39936
	global_load_lds_dwordx4 v[206:207], off
	v_lshl_add_u64 v[206:207], s[46:47], 0, v[134:135]
	s_mov_b32 m0, s66
	s_nop 0
	global_load_lds_dwordx4 v[206:207], off
	s_waitcnt vmcnt(8)
	s_waitcnt lgkmcnt(0)
	s_barrier
	s_setprio 1
	s_waitcnt lgkmcnt(0)
	v_mfma_f32_16x16x32_bf16 v[126:129], v[142:145], v[188:191], v[126:129]
	v_mfma_f32_16x16x32_bf16 v[122:125], v[158:161], v[188:191], v[122:125]
	v_mfma_f32_16x16x32_bf16 v[110:113], v[142:145], v[196:199], v[110:113]
	v_mfma_f32_16x16x32_bf16 v[106:109], v[158:161], v[196:199], v[106:109]
	v_mfma_f32_16x16x32_bf16 v[94:97], v[142:145], v[216:219], v[94:97]
	v_mfma_f32_16x16x32_bf16 v[90:93], v[158:161], v[216:219], v[90:93]
	v_mfma_f32_16x16x32_bf16 v[78:81], v[142:145], v[224:227], v[78:81]
	v_mfma_f32_16x16x32_bf16 v[74:77], v[158:161], v[224:227], v[74:77]
	v_mfma_f32_16x16x32_bf16 v[126:129], v[148:151], v[192:195], v[126:129]
	v_mfma_f32_16x16x32_bf16 v[122:125], v[168:171], v[192:195], v[122:125]
	v_mfma_f32_16x16x32_bf16 v[110:113], v[148:151], v[208:211], v[110:113]
	v_mfma_f32_16x16x32_bf16 v[106:109], v[168:171], v[208:211], v[106:109]
	v_mfma_f32_16x16x32_bf16 v[94:97], v[148:151], v[220:223], v[94:97]
	v_mfma_f32_16x16x32_bf16 v[90:93], v[168:171], v[220:223], v[90:93]
	v_mfma_f32_16x16x32_bf16 v[78:81], v[148:151], v[228:231], v[78:81]
	v_mfma_f32_16x16x32_bf16 v[74:77], v[168:171], v[228:231], v[74:77]
	v_mfma_f32_16x16x32_bf16 v[118:121], v[172:175], v[188:191], v[118:121]
	v_mfma_f32_16x16x32_bf16 v[114:117], v[180:183], v[188:191], v[114:117]
	v_mfma_f32_16x16x32_bf16 v[102:105], v[172:175], v[196:199], v[102:105]
	v_mfma_f32_16x16x32_bf16 v[98:101], v[180:183], v[196:199], v[98:101]
	v_mfma_f32_16x16x32_bf16 v[86:89], v[172:175], v[216:219], v[86:89]
	v_mfma_f32_16x16x32_bf16 v[82:85], v[180:183], v[216:219], v[82:85]
	v_mfma_f32_16x16x32_bf16 v[70:73], v[172:175], v[224:227], v[70:73]
	v_mfma_f32_16x16x32_bf16 v[66:69], v[180:183], v[224:227], v[66:69]
	v_mfma_f32_16x16x32_bf16 v[118:121], v[176:179], v[192:195], v[118:121]
	v_mfma_f32_16x16x32_bf16 v[114:117], v[184:187], v[192:195], v[114:117]
	v_mfma_f32_16x16x32_bf16 v[102:105], v[176:179], v[208:211], v[102:105]
	v_mfma_f32_16x16x32_bf16 v[98:101], v[184:187], v[208:211], v[98:101]
	v_mfma_f32_16x16x32_bf16 v[86:89], v[176:179], v[220:223], v[86:89]
	v_mfma_f32_16x16x32_bf16 v[82:85], v[184:187], v[220:223], v[82:85]
	v_mfma_f32_16x16x32_bf16 v[70:73], v[176:179], v[228:231], v[70:73]
	v_mfma_f32_16x16x32_bf16 v[66:69], v[184:187], v[228:231], v[66:69]
	s_setprio 0
	s_barrier
; #define PG8_STAGE(bufoff, gbase, voff) do { _Pragma("unroll") for (int _i = 0; _i < 2; ++_i) \
;         __builtin_amdgcn_global_load_lds((const unsigned*)((const char*)(gbase) + (voff)[_i]), (PG8_LAS unsigned*)(lds + (bufoff) + ldsw + _i * 8192), 16, 0, 0); } while (0)
; #define PG8_LDA(dst, b, h) do { _Pragma("unroll") for (int m = 0; m < 4; ++m) _Pragma("unroll") for (int k = 0; k < 2; ++k) dst[m][k] = *(const PG8_LAS bf16x8*)(lds + PG8_SA(b, h) + aoff + m * 2048 + k * 1024); } while (0)
; #define PG8_LDB(dst, b, h) do { _Pragma("unroll") for (int n = 0; n < 2; ++n) _Pragma("unroll") for (int k = 0; k < 2; ++k) dst[n][k] = *(const PG8_LAS bf16x8*)(lds + PG8_SB(b, h) + boff + n * 2048 + k * 1024); } while (0)
; #define PG8_BAR __builtin_amdgcn_s_barrier()
; template <class Epi, bool ALIGN_EPI = true>
; __device__ __forceinline__ void gemm_phase(PG8_LAS unsigned char* lds, const Gemm g, const StaticOrder& S, const Epi& E) {
;     ...
;         for (int t = 0; t < nt; t += 2) {
;             const bool last = (t == nt - 2);
;             const char* a1 = cA + (size_t)(t + 1) * kstep;
;             const char* a2 = last ? nA : cA + (size_t)(t + 2) * kstep; const char* b2 = last ? nB : cB + (size_t)(t + 2) * kstep;
;             const char* a3 = a2 + kstep; const char* b3 = b2 + kstep;
;             PG8_LDB(B0, 0, 0); PG8_LDB(B1, 0, 1); PG8_SCHED; PG8_LDA(At, 0, 0); PG8_STAGE(PG8_SA(1, 1), a1 + hstepA, voffA);
;             PG8_WAIT_V(8); PG8_WAIT_L(0); PG8_BAR; PG8_MMA(0, 0, At, B0); PG8_MMA(0, 1, At, B1); PG8_BAR; PG8_SCHED;
;             PG8_LDA(At, 0, 1); PG8_STAGE(PG8_SB(0, 0), b2, voffB); PG8_STAGE(PG8_SB(0, 1), b2 + hstepB, voffB); PG8_STAGE(PG8_SA(0, 0), a2, voffA);
;             PG8_WAIT_V(8); PG8_WAIT_L(0); PG8_BAR; PG8_MMA(1, 0, At, B0); PG8_MMA(1, 1, At, B1); PG8_BAR; PG8_SCHED;
;             PG8_LDB(B0, 1, 0); PG8_LDB(B1, 1, 1); PG8_SCHED; PG8_LDA(At, 1, 0); PG8_STAGE(PG8_SA(0, 1), a2 + hstepA, voffA);
;             PG8_WAIT_V(8); PG8_WAIT_L(0); PG8_BAR; PG8_MMA(0, 0, At, B0); PG8_MMA(0, 1, At, B1); PG8_BAR; PG8_SCHED;
;             PG8_LDA(At, 1, 1); PG8_STAGE(PG8_SB(1, 0), b3, voffB); PG8_STAGE(PG8_SB(1, 1), b3 + hstepB, voffB); PG8_STAGE(PG8_SA(1, 0), a3, voffA);
;             PG8_WAIT_V(8); PG8_WAIT_L(0); PG8_BAR; PG8_MMA(1, 0, At, B0); PG8_MMA(1, 1, At, B1); PG8_BAR; PG8_SCHED;
;         }
;         if constexpr (ALIGN_EPI) { if (wr == 0) PG8_BAR; }
	s_add_i32 s43, s43, s51
	v_lshl_add_u64 v[146:147], v[146:147], 0, s[60:61]
	s_mov_b32 m0, s43
	ds_read_b128 v[188:191], v167 offset:49152
	ds_read_b128 v[192:195], v167 offset:50176
	ds_read_b128 v[196:199], v167 offset:51200
	ds_read_b128 v[208:211], v167 offset:52224
	ds_read_b128 v[216:219], v167 offset:53248
	ds_read_b128 v[220:223], v167 offset:54272
	ds_read_b128 v[224:227], v167 offset:55296
	ds_read_b128 v[228:231], v167 offset:56320
	global_load_lds_dwordx4 v[146:147], off
	s_add_i32 m0, s43, 0x2000
	s_add_u32 s44, s44, 0x40080
	v_lshl_add_u64 v[146:147], v[162:163], 0, s[60:61]
	s_addc_u32 s45, s45, 0
	s_add_i32 s43, s75, s51
	global_load_lds_dwordx4 v[146:147], off
	v_lshl_add_u64 v[146:147], s[44:45], 0, v[132:133]
	s_mov_b32 m0, s43
	s_nop 0
	global_load_lds_dwordx4 v[146:147], off
	v_lshl_add_u64 v[146:147], s[44:45], 0, v[136:137]
	s_add_i32 m0, s43, 0x2000
	s_nop 0
	global_load_lds_dwordx4 v[146:147], off
	v_lshl_add_u64 v[146:147], v[200:201], 0, s[60:61]
	s_mov_b32 m0, s70
	s_nop 0
	global_load_lds_dwordx4 v[146:147], off
	v_lshl_add_u64 v[146:147], v[204:205], 0, s[60:61]
	s_mov_b32 m0, s71
	s_nop 0
	global_load_lds_dwordx4 v[146:147], off
	s_add_i32 s37, s37, 2
	s_add_u32 s6, s6, 0x100
	s_addc_u32 s7, s7, 0
	s_add_u32 s9, s9, 0x100
	s_addc_u32 s35, s35, 0
	s_add_u32 s43, s6, 0xfffc0080
	s_addc_u32 s44, s7, -1
	s_add_i32 s75, 0, 0x10000
	s_cmp_eq_u32 s37, 12
	s_cselect_b32 s47, s39, s44
	s_cselect_b32 s46, s38, s43
	v_add_u32_e32 v32, s75, v165
	s_cselect_b32 s45, s41, s35
	s_cselect_b32 s44, s40, s9
	s_add_i32 s43, 0, 0x14000
	s_cmp_gt_u32 s37, 13
	s_waitcnt vmcnt(8)
	s_waitcnt lgkmcnt(0)
	s_barrier
	s_setprio 1
	s_waitcnt lgkmcnt(0)
	v_mfma_f32_16x16x32_bf16 v[62:65], v[142:145], v[188:191], v[62:65]
	v_mfma_f32_16x16x32_bf16 v[58:61], v[158:161], v[188:191], v[58:61]
	v_mfma_f32_16x16x32_bf16 v[46:49], v[142:145], v[196:199], v[46:49]
	v_mfma_f32_16x16x32_bf16 v[42:45], v[158:161], v[196:199], v[42:45]
	v_mfma_f32_16x16x32_bf16 v[28:31], v[142:145], v[216:219], v[28:31]
	v_mfma_f32_16x16x32_bf16 v[24:27], v[158:161], v[216:219], v[24:27]
	v_mfma_f32_16x16x32_bf16 v[12:15], v[142:145], v[224:227], v[12:15]
	v_mfma_f32_16x16x32_bf16 v[8:11], v[158:161], v[224:227], v[8:11]
	v_mfma_f32_16x16x32_bf16 v[62:65], v[148:151], v[192:195], v[62:65]
	v_mfma_f32_16x16x32_bf16 v[58:61], v[168:171], v[192:195], v[58:61]
	v_mfma_f32_16x16x32_bf16 v[46:49], v[148:151], v[208:211], v[46:49]
	v_mfma_f32_16x16x32_bf16 v[42:45], v[168:171], v[208:211], v[42:45]
	v_mfma_f32_16x16x32_bf16 v[28:31], v[148:151], v[220:223], v[28:31]
	v_mfma_f32_16x16x32_bf16 v[24:27], v[168:171], v[220:223], v[24:27]
	v_mfma_f32_16x16x32_bf16 v[12:15], v[148:151], v[228:231], v[12:15]
	v_mfma_f32_16x16x32_bf16 v[8:11], v[168:171], v[228:231], v[8:11]
	v_mfma_f32_16x16x32_bf16 v[54:57], v[172:175], v[188:191], v[54:57]
	v_mfma_f32_16x16x32_bf16 v[50:53], v[180:183], v[188:191], v[50:53]
	v_mfma_f32_16x16x32_bf16 v[38:41], v[172:175], v[196:199], v[38:41]
	v_mfma_f32_16x16x32_bf16 v[34:37], v[180:183], v[196:199], v[34:37]
	v_mfma_f32_16x16x32_bf16 v[20:23], v[172:175], v[216:219], v[20:23]
	v_mfma_f32_16x16x32_bf16 v[16:19], v[180:183], v[216:219], v[16:19]
	v_mfma_f32_16x16x32_bf16 v[4:7], v[172:175], v[224:227], v[4:7]
	v_mfma_f32_16x16x32_bf16 v[0:3], v[180:183], v[224:227], v[0:3]
	v_mfma_f32_16x16x32_bf16 v[54:57], v[176:179], v[192:195], v[54:57]
	v_mfma_f32_16x16x32_bf16 v[50:53], v[184:187], v[192:195], v[50:53]
	v_mfma_f32_16x16x32_bf16 v[38:41], v[176:179], v[208:211], v[38:41]
	v_mfma_f32_16x16x32_bf16 v[34:37], v[184:187], v[208:211], v[34:37]
	v_mfma_f32_16x16x32_bf16 v[20:23], v[176:179], v[220:223], v[20:23]
	v_mfma_f32_16x16x32_bf16 v[16:19], v[184:187], v[220:223], v[16:19]
	v_mfma_f32_16x16x32_bf16 v[4:7], v[176:179], v[228:231], v[4:7]
	v_mfma_f32_16x16x32_bf16 v[0:3], v[184:187], v[228:231], v[0:3]
	s_setprio 0
	s_barrier
	s_cbranch_scc0 .Lrot_795
	s_and_b64 vcc, exec, s[26:27]
	s_cbranch_vccz .LBB0_798
	s_barrier

; template <class Epi, bool ALIGN_EPI = true>
; __device__ __forceinline__ void gemm_phase(PG8_LAS unsigned char* lds, const Gemm g, const StaticOrder& S, const Epi& E) {
;     ...
;         const bool has_next = S.next(ui + 1, nxt);
;         const char* nA = has_next ? (const char*)g.A + (size_t)nxt.pm * tstepA + (size_t)nxt.ks * ksA : cA; const char* nB = has_next ? (const char*)g.Bt + (size_t)nxt.pn * tstepB + (size_t)nxt.ks * ksA : cB;
;         for (int t = 0; t < nt; t += 2) {
;             const bool last = (t == nt - 2);
;             const char* a1 = cA + (size_t)(t + 1) * kstep;
;             const char* a2 = last ? nA : cA + (size_t)(t + 2) * kstep; const char* b2 = last ? nB : cB + (size_t)(t + 2) * kstep;
;             const char* a3 = a2 + kstep; const char* b3 = b2 + kstep;
.LBB0_1003:
	s_ashr_i32 s11, s10, 31
	s_lshl_b64 s[12:13], s[10:11], 19
	s_add_u32 s12, s28, s12
	s_addc_u32 s13, s29, s13
	s_and_b64 s[14:15], s[2:3], exec
	s_cselect_b32 s11, s13, s21
	s_cselect_b32 s17, s12, s20
	s_ashr_i32 s9, s8, 31
	s_lshl_b64 s[14:15], s[8:9], 19
	s_add_u32 s14, s30, s14
	s_addc_u32 s15, s31, s15
	s_and_b64 s[24:25], s[2:3], exec
	s_cselect_b32 s9, s15, s23
	s_cselect_b32 s19, s14, s22
	s_add_u32 s20, s20, 0x40080
	s_addc_u32 s21, s21, 0
	s_add_u32 s47, s22, 0x100
	s_addc_u32 s48, s23, 0
	s_mov_b32 s49, -2
; #define PG8_STAGE(bufoff, gbase, voff) do { _Pragma("unroll") for (int _i = 0; _i < 2; ++_i) \
;         __builtin_amdgcn_global_load_lds((const unsigned*)((const char*)(gbase) + (voff)[_i]), (PG8_LAS unsigned*)(lds + (bufoff) + ldsw + _i * 8192), 16, 0, 0); } while (0)
; #define PG8_LDA(dst, b, h) do { _Pragma("unroll") for (int m = 0; m < 4; ++m) _Pragma("unroll") for (int k = 0; k < 2; ++k) dst[m][k] = *(const PG8_LAS bf16x8*)(lds + PG8_SA(b, h) + aoff + m * 2048 + k * 1024); } while (0)
; #define PG8_LDB(dst, b, h) do { _Pragma("unroll") for (int n = 0; n < 2; ++n) _Pragma("unroll") for (int k = 0; k < 2; ++k) dst[n][k] = *(const PG8_LAS bf16x8*)(lds + PG8_SB(b, h) + boff + n * 2048 + k * 1024); } while (0)
; #define PG8_WAIT_V(n) asm volatile("s_waitcnt vmcnt(" #n ")" ::: "memory")
; #define PG8_WAIT_L(n) asm volatile("s_waitcnt lgkmcnt(" #n ")" ::: "memory")
; #define PG8_BAR __builtin_amdgcn_s_barrier()
; #define PG8_SCHED __builtin_amdgcn_sched_barrier(0)
; template <class Epi, bool ALIGN_EPI = true>
; __device__ __forceinline__ void gemm_phase(PG8_LAS unsigned char* lds, const Gemm g, const StaticOrder& S, const Epi& E) {
;     ...
;         for (int t = 0; t < nt; t += 2) {
;             const bool last = (t == nt - 2);
;             const char* a1 = cA + (size_t)(t + 1) * kstep;
;             const char* a2 = last ? nA : cA + (size_t)(t + 2) * kstep; const char* b2 = last ? nB : cB + (size_t)(t + 2) * kstep;
;             const char* a3 = a2 + kstep; const char* b3 = b2 + kstep;
;             PG8_LDB(B0, 0, 0); PG8_LDB(B1, 0, 1); PG8_SCHED; PG8_LDA(At, 0, 0); PG8_STAGE(PG8_SA(1, 1), a1 + hstepA, voffA);
;             PG8_WAIT_V(8); PG8_WAIT_L(0); PG8_BAR; PG8_MMA(0, 0, At, B0); PG8_MMA(0, 1, At, B1); PG8_BAR; PG8_SCHED;
;             PG8_LDA(At, 0, 1); PG8_STAGE(PG8_SB(0, 0), b2, voffB); PG8_STAGE(PG8_SB(0, 1), b2 + hstepB, voffB); PG8_STAGE(PG8_SA(0, 0), a2, voffA);
;             PG8_WAIT_V(8); PG8_WAIT_L(0); PG8_BAR; PG8_MMA(1, 0, At, B0); PG8_MMA(1, 1, At, B1); PG8_BAR; PG8_SCHED;
.LBB0_1004:
	s_add_u32 s22, s20, 0xfffc0080
	s_addc_u32 s23, s21, -1
	s_add_i32 s50, 0, 0x10000
	s_cmp_eq_u32 s49, 12
	s_cselect_b32 s25, s11, s23
	s_cselect_b32 s24, s17, s22
	v_add_u32_e32 v32, s50, v143
	s_cselect_b32 s23, s9, s48
	s_cselect_b32 s22, s19, s47
	s_add_i32 s52, 0, 0x14000
	ds_read_b128 v[130:133], v32
	ds_read_b128 v[134:137], v32 offset:1024
	ds_read_b128 v[164:167], v32 offset:2048
	ds_read_b128 v[168:171], v32 offset:3072
	v_add_u32_e32 v32, s52, v143
	ds_read_b128 v[172:175], v32
	ds_read_b128 v[176:179], v32 offset:1024
	ds_read_b128 v[180:183], v32 offset:2048
	ds_read_b128 v[184:187], v32 offset:3072
	v_lshl_add_u64 v[146:147], s[20:21], 0, v[158:159]
	s_add_i32 m0, s35, 0xc000
	ds_read_b128 v[188:191], v163
	ds_read_b128 v[192:195], v163 offset:1024
	ds_read_b128 v[196:199], v163 offset:2048
	ds_read_b128 v[216:219], v163 offset:3072
	ds_read_b128 v[220:223], v163 offset:4096
	ds_read_b128 v[224:227], v163 offset:5120
	ds_read_b128 v[228:231], v163 offset:6144
	ds_read_b128 v[232:235], v163 offset:7168
	global_load_lds_dwordx4 v[146:147], off
	v_lshl_add_u64 v[146:147], s[20:21], 0, v[160:161]
	s_add_i32 m0, s35, 0xe000
	s_nop 0
	global_load_lds_dwordx4 v[146:147], off
	s_waitcnt vmcnt(8)
	s_waitcnt lgkmcnt(0)
	s_barrier
	s_setprio 1
	s_waitcnt lgkmcnt(0)
	v_mfma_f32_16x16x32_bf16 v[126:129], v[188:191], v[130:133], 0
	v_mfma_f32_16x16x32_bf16 v[122:125], v[188:191], v[164:167], 0
	v_mfma_f32_16x16x32_bf16 v[110:113], v[196:199], v[130:133], 0
	v_mfma_f32_16x16x32_bf16 v[106:109], v[196:199], v[164:167], 0
	v_mfma_f32_16x16x32_bf16 v[94:97], v[220:223], v[130:133], 0
	v_mfma_f32_16x16x32_bf16 v[90:93], v[220:223], v[164:167], 0
	v_mfma_f32_16x16x32_bf16 v[78:81], v[228:231], v[130:133], 0
	v_mfma_f32_16x16x32_bf16 v[74:77], v[228:231], v[164:167], 0
	v_mfma_f32_16x16x32_bf16 v[126:129], v[192:195], v[134:137], v[126:129]
	v_mfma_f32_16x16x32_bf16 v[122:125], v[192:195], v[168:171], v[122:125]
	v_mfma_f32_16x16x32_bf16 v[110:113], v[216:219], v[134:137], v[110:113]
	v_mfma_f32_16x16x32_bf16 v[106:109], v[216:219], v[168:171], v[106:109]
	v_mfma_f32_16x16x32_bf16 v[94:97], v[224:227], v[134:137], v[94:97]
	v_mfma_f32_16x16x32_bf16 v[90:93], v[224:227], v[168:171], v[90:93]
	v_mfma_f32_16x16x32_bf16 v[78:81], v[232:235], v[134:137], v[78:81]
	v_mfma_f32_16x16x32_bf16 v[74:77], v[232:235], v[168:171], v[74:77]
	v_mfma_f32_16x16x32_bf16 v[118:121], v[188:191], v[172:175], 0
	v_mfma_f32_16x16x32_bf16 v[114:117], v[188:191], v[180:183], 0
	v_mfma_f32_16x16x32_bf16 v[102:105], v[196:199], v[172:175], 0
	v_mfma_f32_16x16x32_bf16 v[98:101], v[196:199], v[180:183], 0
	v_mfma_f32_16x16x32_bf16 v[86:89], v[220:223], v[172:175], 0
	v_mfma_f32_16x16x32_bf16 v[82:85], v[220:223], v[180:183], 0
	v_mfma_f32_16x16x32_bf16 v[70:73], v[228:231], v[172:175], 0
	v_mfma_f32_16x16x32_bf16 v[66:69], v[228:231], v[180:183], 0
	v_mfma_f32_16x16x32_bf16 v[118:121], v[192:195], v[176:179], v[118:121]
	v_mfma_f32_16x16x32_bf16 v[114:117], v[192:195], v[184:187], v[114:117]
	v_mfma_f32_16x16x32_bf16 v[102:105], v[216:219], v[176:179], v[102:105]
	v_mfma_f32_16x16x32_bf16 v[98:101], v[216:219], v[184:187], v[98:101]
	v_mfma_f32_16x16x32_bf16 v[86:89], v[224:227], v[176:179], v[86:89]
	v_mfma_f32_16x16x32_bf16 v[82:85], v[224:227], v[184:187], v[82:85]
	v_mfma_f32_16x16x32_bf16 v[70:73], v[232:235], v[176:179], v[70:73]
	v_mfma_f32_16x16x32_bf16 v[66:69], v[232:235], v[184:187], v[66:69]
	s_setprio 0
	s_barrier
	s_add_i32 s50, s50, s34
	v_lshl_add_u64 v[146:147], s[22:23], 0, v[138:139]
	s_mov_b32 m0, s50
	ds_read_b128 v[188:191], v163 offset:16384
	ds_read_b128 v[192:195], v163 offset:17408
	ds_read_b128 v[196:199], v163 offset:18432
	ds_read_b128 v[216:219], v163 offset:19456
	ds_read_b128 v[220:223], v163 offset:20480
	ds_read_b128 v[224:227], v163 offset:21504
	ds_read_b128 v[228:231], v163 offset:22528
	ds_read_b128 v[232:235], v163 offset:23552
	global_load_lds_dwordx4 v[146:147], off
	s_add_i32 m0, s50, 0x2000
	s_add_u32 s50, s22, 0x40000
	v_lshl_add_u64 v[148:149], s[22:23], 0, v[140:141]
	s_addc_u32 s51, s23, 0
	s_add_i32 s52, s52, s34
	global_load_lds_dwordx4 v[148:149], off
	v_lshl_add_u64 v[150:151], s[50:51], 0, v[138:139]
	s_mov_b32 m0, s52
	v_lshl_add_u64 v[200:201], s[24:25], 0, v[140:141]
	global_load_lds_dwordx4 v[150:151], off
	v_lshl_add_u64 v[150:151], s[50:51], 0, v[140:141]
	s_add_i32 m0, s52, 0x2000
	s_nop 0
	global_load_lds_dwordx4 v[150:151], off
	v_lshl_add_u64 v[150:151], s[24:25], 0, v[138:139]
	s_mov_b32 m0, s35
	s_nop 0
	global_load_lds_dwordx4 v[150:151], off
	s_mov_b32 m0, s36
	s_nop 0
	global_load_lds_dwordx4 v[200:201], off
	s_waitcnt vmcnt(8)
	s_waitcnt lgkmcnt(0)
	s_barrier
	s_setprio 1
	s_waitcnt lgkmcnt(0)
	v_mfma_f32_16x16x32_bf16 v[62:65], v[188:191], v[130:133], 0
	v_mfma_f32_16x16x32_bf16 v[58:61], v[188:191], v[164:167], 0
	v_mfma_f32_16x16x32_bf16 v[46:49], v[196:199], v[130:133], 0
	v_mfma_f32_16x16x32_bf16 v[42:45], v[196:199], v[164:167], 0
	v_mfma_f32_16x16x32_bf16 v[28:31], v[220:223], v[130:133], 0
	v_mfma_f32_16x16x32_bf16 v[24:27], v[220:223], v[164:167], 0
	v_mfma_f32_16x16x32_bf16 v[12:15], v[228:231], v[130:133], 0
	v_mfma_f32_16x16x32_bf16 v[8:11], v[228:231], v[164:167], 0
	v_mfma_f32_16x16x32_bf16 v[62:65], v[192:195], v[134:137], v[62:65]
	v_mfma_f32_16x16x32_bf16 v[58:61], v[192:195], v[168:171], v[58:61]
	v_mfma_f32_16x16x32_bf16 v[46:49], v[216:219], v[134:137], v[46:49]
	v_mfma_f32_16x16x32_bf16 v[42:45], v[216:219], v[168:171], v[42:45]
	v_mfma_f32_16x16x32_bf16 v[28:31], v[224:227], v[134:137], v[28:31]
	v_mfma_f32_16x16x32_bf16 v[24:27], v[224:227], v[168:171], v[24:27]
	v_mfma_f32_16x16x32_bf16 v[12:15], v[232:235], v[134:137], v[12:15]
	v_mfma_f32_16x16x32_bf16 v[8:11], v[232:235], v[168:171], v[8:11]
	v_mfma_f32_16x16x32_bf16 v[54:57], v[188:191], v[172:175], 0
	v_mfma_f32_16x16x32_bf16 v[50:53], v[188:191], v[180:183], 0
	v_mfma_f32_16x16x32_bf16 v[38:41], v[196:199], v[172:175], 0
	v_mfma_f32_16x16x32_bf16 v[34:37], v[196:199], v[180:183], 0
	v_mfma_f32_16x16x32_bf16 v[20:23], v[220:223], v[172:175], 0
	v_mfma_f32_16x16x32_bf16 v[16:19], v[220:223], v[180:183], 0
	v_mfma_f32_16x16x32_bf16 v[4:7], v[228:231], v[172:175], 0
	v_mfma_f32_16x16x32_bf16 v[0:3], v[228:231], v[180:183], 0
	v_mfma_f32_16x16x32_bf16 v[54:57], v[192:195], v[176:179], v[54:57]
	v_mfma_f32_16x16x32_bf16 v[50:53], v[192:195], v[184:187], v[50:53]
	v_mfma_f32_16x16x32_bf16 v[38:41], v[216:219], v[176:179], v[38:41]
	v_mfma_f32_16x16x32_bf16 v[34:37], v[216:219], v[184:187], v[34:37]
	v_mfma_f32_16x16x32_bf16 v[20:23], v[224:227], v[176:179], v[20:23]
	v_mfma_f32_16x16x32_bf16 v[16:19], v[224:227], v[184:187], v[16:19]
	v_mfma_f32_16x16x32_bf16 v[4:7], v[232:235], v[176:179], v[4:7]
	v_mfma_f32_16x16x32_bf16 v[0:3], v[232:235], v[184:187], v[0:3]
	s_setprio 0
	s_barrier
	s_branch .Lp3_1004

; #define PG8_STAGE(bufoff, gbase, voff) do { _Pragma("unroll") for (int _i = 0; _i < 2; ++_i) \
;         __builtin_amdgcn_global_load_lds((const unsigned*)((const char*)(gbase) + (voff)[_i]), (PG8_LAS unsigned*)(lds + (bufoff) + ldsw + _i * 8192), 16, 0, 0); } while (0)
; #define PG8_LDA(dst, b, h) do { _Pragma("unroll") for (int m = 0; m < 4; ++m) _Pragma("unroll") for (int k = 0; k < 2; ++k) dst[m][k] = *(const PG8_LAS bf16x8*)(lds + PG8_SA(b, h) + aoff + m * 2048 + k * 1024); } while (0)
; #define PG8_LDB(dst, b, h) do { _Pragma("unroll") for (int n = 0; n < 2; ++n) _Pragma("unroll") for (int k = 0; k < 2; ++k) dst[n][k] = *(const PG8_LAS bf16x8*)(lds + PG8_SB(b, h) + boff + n * 2048 + k * 1024); } while (0)
; #define PG8_WAIT_V(n) asm volatile("s_waitcnt vmcnt(" #n ")" ::: "memory")
; #define PG8_WAIT_L(n) asm volatile("s_waitcnt lgkmcnt(" #n ")" ::: "memory")
; #define PG8_BAR __builtin_amdgcn_s_barrier()
; #define PG8_SCHED __builtin_amdgcn_sched_barrier(0)
; template <class Epi, bool ALIGN_EPI = true>
; __device__ __forceinline__ void gemm_phase(PG8_LAS unsigned char* lds, const Gemm g, const StaticOrder& S, const Epi& E) {
;     ...
;             PG8_LDB(B0, 1, 0); PG8_LDB(B1, 1, 1); PG8_SCHED; PG8_LDA(At, 1, 0); PG8_STAGE(PG8_SA(0, 1), a2 + hstepA, voffA);
;             PG8_WAIT_V(8); PG8_WAIT_L(0); PG8_BAR; PG8_MMA(0, 0, At, B0); PG8_MMA(0, 1, At, B1); PG8_BAR; PG8_SCHED;
.Lp3_1004:
	s_add_i32 s50, 0, 0x18000
	v_add_u32_e32 v32, s50, v143
	s_add_i32 s51, 0, 0x1c000
	ds_read_b128 v[130:133], v32
	ds_read_b128 v[134:137], v32 offset:1024
	ds_read_b128 v[164:167], v32 offset:2048
	ds_read_b128 v[168:171], v32 offset:3072
	v_add_u32_e32 v32, s51, v143
	ds_read_b128 v[172:175], v32
	ds_read_b128 v[176:179], v32 offset:1024
	ds_read_b128 v[180:183], v32 offset:2048
	ds_read_b128 v[184:187], v32 offset:3072
	s_add_u32 s24, s24, 0x40000
	s_addc_u32 s25, s25, 0
	s_mov_b32 m0, s37
	v_lshl_add_u64 v[204:205], s[24:25], 0, v[138:139]
	ds_read_b128 v[188:191], v163 offset:32768
	ds_read_b128 v[192:195], v163 offset:33792
	ds_read_b128 v[196:199], v163 offset:34816
	ds_read_b128 v[216:219], v163 offset:35840
	ds_read_b128 v[220:223], v163 offset:36864
	ds_read_b128 v[224:227], v163 offset:37888
	ds_read_b128 v[228:231], v163 offset:38912
	ds_read_b128 v[232:235], v163 offset:39936
	global_load_lds_dwordx4 v[204:205], off
	v_lshl_add_u64 v[204:205], s[24:25], 0, v[140:141]
	s_mov_b32 m0, s38
	s_nop 0
	global_load_lds_dwordx4 v[204:205], off
	s_waitcnt vmcnt(8)
	s_waitcnt lgkmcnt(0)
	s_barrier
	s_setprio 1
	s_waitcnt lgkmcnt(0)
	v_mfma_f32_16x16x32_bf16 v[126:129], v[188:191], v[130:133], v[126:129]
	v_mfma_f32_16x16x32_bf16 v[122:125], v[188:191], v[164:167], v[122:125]
	v_mfma_f32_16x16x32_bf16 v[110:113], v[196:199], v[130:133], v[110:113]
	v_mfma_f32_16x16x32_bf16 v[106:109], v[196:199], v[164:167], v[106:109]
	v_mfma_f32_16x16x32_bf16 v[94:97], v[220:223], v[130:133], v[94:97]
	v_mfma_f32_16x16x32_bf16 v[90:93], v[220:223], v[164:167], v[90:93]
	v_mfma_f32_16x16x32_bf16 v[78:81], v[228:231], v[130:133], v[78:81]
	v_mfma_f32_16x16x32_bf16 v[74:77], v[228:231], v[164:167], v[74:77]
	v_mfma_f32_16x16x32_bf16 v[126:129], v[192:195], v[134:137], v[126:129]
	v_mfma_f32_16x16x32_bf16 v[122:125], v[192:195], v[168:171], v[122:125]
	v_mfma_f32_16x16x32_bf16 v[110:113], v[216:219], v[134:137], v[110:113]
	v_mfma_f32_16x16x32_bf16 v[106:109], v[216:219], v[168:171], v[106:109]
	v_mfma_f32_16x16x32_bf16 v[94:97], v[224:227], v[134:137], v[94:97]
	v_mfma_f32_16x16x32_bf16 v[90:93], v[224:227], v[168:171], v[90:93]
	v_mfma_f32_16x16x32_bf16 v[78:81], v[232:235], v[134:137], v[78:81]
	v_mfma_f32_16x16x32_bf16 v[74:77], v[232:235], v[168:171], v[74:77]
	v_mfma_f32_16x16x32_bf16 v[118:121], v[188:191], v[172:175], v[118:121]
	v_mfma_f32_16x16x32_bf16 v[114:117], v[188:191], v[180:183], v[114:117]
	v_mfma_f32_16x16x32_bf16 v[102:105], v[196:199], v[172:175], v[102:105]
	v_mfma_f32_16x16x32_bf16 v[98:101], v[196:199], v[180:183], v[98:101]
	v_mfma_f32_16x16x32_bf16 v[86:89], v[220:223], v[172:175], v[86:89]
	v_mfma_f32_16x16x32_bf16 v[82:85], v[220:223], v[180:183], v[82:85]
	v_mfma_f32_16x16x32_bf16 v[70:73], v[228:231], v[172:175], v[70:73]
	v_mfma_f32_16x16x32_bf16 v[66:69], v[228:231], v[180:183], v[66:69]
	v_mfma_f32_16x16x32_bf16 v[118:121], v[192:195], v[176:179], v[118:121]
	v_mfma_f32_16x16x32_bf16 v[114:117], v[192:195], v[184:187], v[114:117]
	v_mfma_f32_16x16x32_bf16 v[102:105], v[216:219], v[176:179], v[102:105]
	v_mfma_f32_16x16x32_bf16 v[98:101], v[216:219], v[184:187], v[98:101]
	v_mfma_f32_16x16x32_bf16 v[86:89], v[224:227], v[176:179], v[86:89]
	v_mfma_f32_16x16x32_bf16 v[82:85], v[224:227], v[184:187], v[82:85]
	v_mfma_f32_16x16x32_bf16 v[70:73], v[232:235], v[176:179], v[70:73]
	v_mfma_f32_16x16x32_bf16 v[66:69], v[232:235], v[184:187], v[66:69]
	s_setprio 0
	s_barrier
; #define PG8_STAGE(bufoff, gbase, voff) do { _Pragma("unroll") for (int _i = 0; _i < 2; ++_i) \
;         __builtin_amdgcn_global_load_lds((const unsigned*)((const char*)(gbase) + (voff)[_i]), (PG8_LAS unsigned*)(lds + (bufoff) + ldsw + _i * 8192), 16, 0, 0); } while (0)
; #define PG8_LDA(dst, b, h) do { _Pragma("unroll") for (int m = 0; m < 4; ++m) _Pragma("unroll") for (int k = 0; k < 2; ++k) dst[m][k] = *(const PG8_LAS bf16x8*)(lds + PG8_SA(b, h) + aoff + m * 2048 + k * 1024); } while (0)
; #define PG8_LDB(dst, b, h) do { _Pragma("unroll") for (int n = 0; n < 2; ++n) _Pragma("unroll") for (int k = 0; k < 2; ++k) dst[n][k] = *(const PG8_LAS bf16x8*)(lds + PG8_SB(b, h) + boff + n * 2048 + k * 1024); } while (0)
; #define PG8_BAR __builtin_amdgcn_s_barrier()
; template <class Epi, bool ALIGN_EPI = true>
; __device__ __forceinline__ void gemm_phase(PG8_LAS unsigned char* lds, const Gemm g, const StaticOrder& S, const Epi& E) {
;     ...
;         for (int t = 0; t < nt; t += 2) {
;             const bool last = (t == nt - 2);
;             const char* a1 = cA + (size_t)(t + 1) * kstep;
;             const char* a2 = last ? nA : cA + (size_t)(t + 2) * kstep; const char* b2 = last ? nB : cB + (size_t)(t + 2) * kstep;
;             const char* a3 = a2 + kstep; const char* b3 = b2 + kstep;
;             PG8_LDB(B0, 0, 0); PG8_LDB(B1, 0, 1); PG8_SCHED; PG8_LDA(At, 0, 0); PG8_STAGE(PG8_SA(1, 1), a1 + hstepA, voffA);
;             PG8_WAIT_V(8); PG8_WAIT_L(0); PG8_BAR; PG8_MMA(0, 0, At, B0); PG8_MMA(0, 1, At, B1); PG8_BAR; PG8_SCHED;
;             PG8_LDA(At, 0, 1); PG8_STAGE(PG8_SB(0, 0), b2, voffB); PG8_STAGE(PG8_SB(0, 1), b2 + hstepB, voffB); PG8_STAGE(PG8_SA(0, 0), a2, voffA);
;             PG8_WAIT_V(8); PG8_WAIT_L(0); PG8_BAR; PG8_MMA(1, 0, At, B0); PG8_MMA(1, 1, At, B1); PG8_BAR; PG8_SCHED;
;             PG8_LDB(B0, 1, 0); PG8_LDB(B1, 1, 1); PG8_SCHED; PG8_LDA(At, 1, 0); PG8_STAGE(PG8_SA(0, 1), a2 + hstepA, voffA);
;             PG8_WAIT_V(8); PG8_WAIT_L(0); PG8_BAR; PG8_MMA(0, 0, At, B0); PG8_MMA(0, 1, At, B1); PG8_BAR; PG8_SCHED;
;             PG8_LDA(At, 1, 1); PG8_STAGE(PG8_SB(1, 0), b3, voffB); PG8_STAGE(PG8_SB(1, 1), b3 + hstepB, voffB); PG8_STAGE(PG8_SA(1, 0), a3, voffA);
;             PG8_WAIT_V(8); PG8_WAIT_L(0); PG8_BAR; PG8_MMA(1, 0, At, B0); PG8_MMA(1, 1, At, B1); PG8_BAR; PG8_SCHED;
;         }
;         if constexpr (ALIGN_EPI) { if (wr == 0) PG8_BAR; }
	s_add_i32 s24, s50, s34
	v_lshl_add_u64 v[146:147], v[146:147], 0, s[60:61]
	s_mov_b32 m0, s24
	ds_read_b128 v[188:191], v163 offset:49152
	ds_read_b128 v[192:195], v163 offset:50176
	ds_read_b128 v[196:199], v163 offset:51200
	ds_read_b128 v[216:219], v163 offset:52224
	ds_read_b128 v[220:223], v163 offset:53248
	ds_read_b128 v[224:227], v163 offset:54272
	ds_read_b128 v[228:231], v163 offset:55296
	ds_read_b128 v[232:235], v163 offset:56320
	global_load_lds_dwordx4 v[146:147], off
	s_add_i32 m0, s24, 0x2000
	s_add_u32 s22, s22, 0x40080
	v_lshl_add_u64 v[146:147], v[148:149], 0, s[60:61]
	s_addc_u32 s23, s23, 0
	s_add_i32 s24, s51, s34
	global_load_lds_dwordx4 v[146:147], off
	v_lshl_add_u64 v[146:147], s[22:23], 0, v[138:139]
	s_mov_b32 m0, s24
	s_nop 0
	global_load_lds_dwordx4 v[146:147], off
	v_lshl_add_u64 v[146:147], s[22:23], 0, v[140:141]
	s_add_i32 m0, s24, 0x2000
	s_nop 0
	global_load_lds_dwordx4 v[146:147], off
	v_lshl_add_u64 v[146:147], v[150:151], 0, s[60:61]
	s_mov_b32 m0, s42
	s_nop 0
	global_load_lds_dwordx4 v[146:147], off
	v_lshl_add_u64 v[146:147], v[200:201], 0, s[60:61]
	s_mov_b32 m0, s43
	s_nop 0
	global_load_lds_dwordx4 v[146:147], off
	s_add_i32 s49, s49, 2
	s_add_u32 s20, s20, 0x100
	s_addc_u32 s21, s21, 0
	s_add_u32 s47, s47, 0x100
	s_addc_u32 s48, s48, 0
	s_add_u32 s22, s20, 0xfffc0080
	s_addc_u32 s23, s21, -1
	s_add_i32 s50, 0, 0x10000
	s_cmp_eq_u32 s49, 12
	s_cselect_b32 s25, s11, s23
	s_cselect_b32 s24, s17, s22
	v_add_u32_e32 v32, s50, v143
	s_cselect_b32 s23, s9, s48
	s_cselect_b32 s22, s19, s47
	s_add_i32 s52, 0, 0x14000
	s_cmp_gt_u32 s49, 13
	s_waitcnt vmcnt(8)
	s_waitcnt lgkmcnt(0)
	s_barrier
	s_setprio 1
	s_waitcnt lgkmcnt(0)
	v_mfma_f32_16x16x32_bf16 v[62:65], v[188:191], v[130:133], v[62:65]
	v_mfma_f32_16x16x32_bf16 v[58:61], v[188:191], v[164:167], v[58:61]
	v_mfma_f32_16x16x32_bf16 v[46:49], v[196:199], v[130:133], v[46:49]
	v_mfma_f32_16x16x32_bf16 v[42:45], v[196:199], v[164:167], v[42:45]
	v_mfma_f32_16x16x32_bf16 v[28:31], v[220:223], v[130:133], v[28:31]
	v_mfma_f32_16x16x32_bf16 v[24:27], v[220:223], v[164:167], v[24:27]
	v_mfma_f32_16x16x32_bf16 v[12:15], v[228:231], v[130:133], v[12:15]
	v_mfma_f32_16x16x32_bf16 v[8:11], v[228:231], v[164:167], v[8:11]
	v_mfma_f32_16x16x32_bf16 v[62:65], v[192:195], v[134:137], v[62:65]
	v_mfma_f32_16x16x32_bf16 v[58:61], v[192:195], v[168:171], v[58:61]
	v_mfma_f32_16x16x32_bf16 v[46:49], v[216:219], v[134:137], v[46:49]
	v_mfma_f32_16x16x32_bf16 v[42:45], v[216:219], v[168:171], v[42:45]
	v_mfma_f32_16x16x32_bf16 v[28:31], v[224:227], v[134:137], v[28:31]
	v_mfma_f32_16x16x32_bf16 v[24:27], v[224:227], v[168:171], v[24:27]
	v_mfma_f32_16x16x32_bf16 v[12:15], v[232:235], v[134:137], v[12:15]
	v_mfma_f32_16x16x32_bf16 v[8:11], v[232:235], v[168:171], v[8:11]
	v_mfma_f32_16x16x32_bf16 v[54:57], v[188:191], v[172:175], v[54:57]
	v_mfma_f32_16x16x32_bf16 v[50:53], v[188:191], v[180:183], v[50:53]
	v_mfma_f32_16x16x32_bf16 v[38:41], v[196:199], v[172:175], v[38:41]
	v_mfma_f32_16x16x32_bf16 v[34:37], v[196:199], v[180:183], v[34:37]
	v_mfma_f32_16x16x32_bf16 v[20:23], v[220:223], v[172:175], v[20:23]
	v_mfma_f32_16x16x32_bf16 v[16:19], v[220:223], v[180:183], v[16:19]
	v_mfma_f32_16x16x32_bf16 v[4:7], v[228:231], v[172:175], v[4:7]
	v_mfma_f32_16x16x32_bf16 v[0:3], v[228:231], v[180:183], v[0:3]
	v_mfma_f32_16x16x32_bf16 v[54:57], v[192:195], v[176:179], v[54:57]
	v_mfma_f32_16x16x32_bf16 v[50:53], v[192:195], v[184:187], v[50:53]
	v_mfma_f32_16x16x32_bf16 v[38:41], v[216:219], v[176:179], v[38:41]
	v_mfma_f32_16x16x32_bf16 v[34:37], v[216:219], v[184:187], v[34:37]
	v_mfma_f32_16x16x32_bf16 v[20:23], v[224:227], v[176:179], v[20:23]
	v_mfma_f32_16x16x32_bf16 v[16:19], v[224:227], v[184:187], v[16:19]
	v_mfma_f32_16x16x32_bf16 v[4:7], v[232:235], v[176:179], v[4:7]
	v_mfma_f32_16x16x32_bf16 v[0:3], v[232:235], v[184:187], v[0:3]
	s_setprio 0
	s_barrier
	s_cbranch_scc0 .Lrot_1004
	s_and_b64 vcc, exec, s[6:7]
	s_cbranch_vccz .LBB0_1007
	s_barrier

; template <class Epi, bool ALIGN_EPI = true>
; __device__ __forceinline__ void gemm_phase(PG8_LAS unsigned char* lds, const Gemm g, const StaticOrder& S, const Epi& E) {
;     ...
;         const bool has_next = S.next(ui + 1, nxt);
;         const char* nA = has_next ? (const char*)g.A + (size_t)nxt.pm * tstepA + (size_t)nxt.ks * ksA : cA; const char* nB = has_next ? (const char*)g.Bt + (size_t)nxt.pn * tstepB + (size_t)nxt.ks * ksA : cB;
;         for (int t = 0; t < nt; t += 2) {
;             const bool last = (t == nt - 2);
;             const char* a1 = cA + (size_t)(t + 1) * kstep;
;             const char* a2 = last ? nA : cA + (size_t)(t + 2) * kstep; const char* b2 = last ? nB : cB + (size_t)(t + 2) * kstep;
;             const char* a3 = a2 + kstep; const char* b3 = b2 + kstep;
.LBB0_1828:
	s_ashr_i32 s37, s36, 31
	s_lshl_b64 s[6:7], s[36:37], 19
	s_add_u32 s9, s56, s6
	s_addc_u32 s35, s58, s7
	s_and_b64 s[6:7], s[4:5], exec
	s_cselect_b32 s39, s35, s47
	s_cselect_b32 s38, s9, s46
	s_ashr_i32 s35, s34, 31
	s_lshl_b64 s[6:7], s[34:35], 19
	s_add_u32 s9, s50, s6
	s_addc_u32 s35, s51, s7
	s_and_b64 s[6:7], s[4:5], exec
	s_cselect_b32 s41, s35, s45
	s_cselect_b32 s40, s9, s44
	s_add_u32 s6, s46, 0x40080
	s_addc_u32 s7, s47, 0
	s_add_u32 s9, s44, 0x100
	s_addc_u32 s35, s45, 0
	s_mov_b32 s37, -2
; #define PG8_STAGE(bufoff, gbase, voff) do { _Pragma("unroll") for (int _i = 0; _i < 2; ++_i) \
;         __builtin_amdgcn_global_load_lds((const unsigned*)((const char*)(gbase) + (voff)[_i]), (PG8_LAS unsigned*)(lds + (bufoff) + ldsw + _i * 8192), 16, 0, 0); } while (0)
; #define PG8_LDA(dst, b, h) do { _Pragma("unroll") for (int m = 0; m < 4; ++m) _Pragma("unroll") for (int k = 0; k < 2; ++k) dst[m][k] = *(const PG8_LAS bf16x8*)(lds + PG8_SA(b, h) + aoff + m * 2048 + k * 1024); } while (0)
; #define PG8_LDB(dst, b, h) do { _Pragma("unroll") for (int n = 0; n < 2; ++n) _Pragma("unroll") for (int k = 0; k < 2; ++k) dst[n][k] = *(const PG8_LAS bf16x8*)(lds + PG8_SB(b, h) + boff + n * 2048 + k * 1024); } while (0)
; #define PG8_WAIT_V(n) asm volatile("s_waitcnt vmcnt(" #n ")" ::: "memory")
; #define PG8_WAIT_L(n) asm volatile("s_waitcnt lgkmcnt(" #n ")" ::: "memory")
; #define PG8_BAR __builtin_amdgcn_s_barrier()
; #define PG8_SCHED __builtin_amdgcn_sched_barrier(0)
; template <class Epi, bool ALIGN_EPI = true>
; __device__ __forceinline__ void gemm_phase(PG8_LAS unsigned char* lds, const Gemm g, const StaticOrder& S, const Epi& E) {
;     ...
;         for (int t = 0; t < nt; t += 2) {
;             const bool last = (t == nt - 2);
;             const char* a1 = cA + (size_t)(t + 1) * kstep;
;             const char* a2 = last ? nA : cA + (size_t)(t + 2) * kstep; const char* b2 = last ? nB : cB + (size_t)(t + 2) * kstep;
;             const char* a3 = a2 + kstep; const char* b3 = b2 + kstep;
;             PG8_LDB(B0, 0, 0); PG8_LDB(B1, 0, 1); PG8_SCHED; PG8_LDA(At, 0, 0); PG8_STAGE(PG8_SA(1, 1), a1 + hstepA, voffA);
;             PG8_WAIT_V(8); PG8_WAIT_L(0); PG8_BAR; PG8_MMA(0, 0, At, B0); PG8_MMA(0, 1, At, B1); PG8_BAR; PG8_SCHED;
;             PG8_LDA(At, 0, 1); PG8_STAGE(PG8_SB(0, 0), b2, voffB); PG8_STAGE(PG8_SB(0, 1), b2 + hstepB, voffB); PG8_STAGE(PG8_SA(0, 0), a2, voffA);
;             PG8_WAIT_V(8); PG8_WAIT_L(0); PG8_BAR; PG8_MMA(1, 0, At, B0); PG8_MMA(1, 1, At, B1); PG8_BAR; PG8_SCHED;
.LBB0_1829:
	s_add_u32 s43, s6, 0xfffc0080
	s_addc_u32 s44, s7, -1
	s_add_i32 s75, 0, 0x10000
	s_cmp_eq_u32 s37, 12
	s_cselect_b32 s47, s39, s44
	s_cselect_b32 s46, s38, s43
	v_add_u32_e32 v32, s75, v165
	s_cselect_b32 s45, s41, s35
	s_cselect_b32 s44, s40, s9
	s_add_i32 s43, 0, 0x14000
	ds_read_b128 v[142:145], v32
	ds_read_b128 v[148:151], v32 offset:1024
	ds_read_b128 v[158:161], v32 offset:2048
	ds_read_b128 v[168:171], v32 offset:3072
	v_add_u32_e32 v32, s43, v165
	ds_read_b128 v[172:175], v32
	ds_read_b128 v[176:179], v32 offset:1024
	ds_read_b128 v[180:183], v32 offset:2048
	ds_read_b128 v[184:187], v32 offset:3072
	v_lshl_add_u64 v[146:147], s[6:7], 0, v[138:139]
	s_add_i32 m0, s59, 0xc000
	ds_read_b128 v[188:191], v167
	ds_read_b128 v[192:195], v167 offset:1024
	ds_read_b128 v[196:199], v167 offset:2048
	ds_read_b128 v[208:211], v167 offset:3072
	ds_read_b128 v[216:219], v167 offset:4096
	ds_read_b128 v[220:223], v167 offset:5120
	ds_read_b128 v[224:227], v167 offset:6144
	ds_read_b128 v[228:231], v167 offset:7168
	global_load_lds_dwordx4 v[146:147], off
	v_lshl_add_u64 v[146:147], s[6:7], 0, v[140:141]
	s_add_i32 m0, s59, 0xe000
	s_nop 0
	global_load_lds_dwordx4 v[146:147], off
	s_waitcnt vmcnt(8)
	s_waitcnt lgkmcnt(0)
	s_barrier
	s_setprio 1
	s_waitcnt lgkmcnt(0)
	v_mfma_f32_16x16x32_bf16 v[126:129], v[142:145], v[188:191], 0
	v_mfma_f32_16x16x32_bf16 v[122:125], v[158:161], v[188:191], 0
	v_mfma_f32_16x16x32_bf16 v[110:113], v[142:145], v[196:199], 0
	v_mfma_f32_16x16x32_bf16 v[106:109], v[158:161], v[196:199], 0
	v_mfma_f32_16x16x32_bf16 v[94:97], v[142:145], v[216:219], 0
	v_mfma_f32_16x16x32_bf16 v[90:93], v[158:161], v[216:219], 0
	v_mfma_f32_16x16x32_bf16 v[78:81], v[142:145], v[224:227], 0
	v_mfma_f32_16x16x32_bf16 v[74:77], v[158:161], v[224:227], 0
	v_mfma_f32_16x16x32_bf16 v[126:129], v[148:151], v[192:195], v[126:129]
	v_mfma_f32_16x16x32_bf16 v[122:125], v[168:171], v[192:195], v[122:125]
	v_mfma_f32_16x16x32_bf16 v[110:113], v[148:151], v[208:211], v[110:113]
	v_mfma_f32_16x16x32_bf16 v[106:109], v[168:171], v[208:211], v[106:109]
	v_mfma_f32_16x16x32_bf16 v[94:97], v[148:151], v[220:223], v[94:97]
	v_mfma_f32_16x16x32_bf16 v[90:93], v[168:171], v[220:223], v[90:93]
	v_mfma_f32_16x16x32_bf16 v[78:81], v[148:151], v[228:231], v[78:81]
	v_mfma_f32_16x16x32_bf16 v[74:77], v[168:171], v[228:231], v[74:77]
	v_mfma_f32_16x16x32_bf16 v[118:121], v[172:175], v[188:191], 0
	v_mfma_f32_16x16x32_bf16 v[114:117], v[180:183], v[188:191], 0
	v_mfma_f32_16x16x32_bf16 v[102:105], v[172:175], v[196:199], 0
	v_mfma_f32_16x16x32_bf16 v[98:101], v[180:183], v[196:199], 0
	v_mfma_f32_16x16x32_bf16 v[86:89], v[172:175], v[216:219], 0
	v_mfma_f32_16x16x32_bf16 v[82:85], v[180:183], v[216:219], 0
	v_mfma_f32_16x16x32_bf16 v[70:73], v[172:175], v[224:227], 0
	v_mfma_f32_16x16x32_bf16 v[66:69], v[180:183], v[224:227], 0
	v_mfma_f32_16x16x32_bf16 v[118:121], v[176:179], v[192:195], v[118:121]
	v_mfma_f32_16x16x32_bf16 v[114:117], v[184:187], v[192:195], v[114:117]
	v_mfma_f32_16x16x32_bf16 v[102:105], v[176:179], v[208:211], v[102:105]
	v_mfma_f32_16x16x32_bf16 v[98:101], v[184:187], v[208:211], v[98:101]
	v_mfma_f32_16x16x32_bf16 v[86:89], v[176:179], v[220:223], v[86:89]
	v_mfma_f32_16x16x32_bf16 v[82:85], v[184:187], v[220:223], v[82:85]
	v_mfma_f32_16x16x32_bf16 v[70:73], v[176:179], v[228:231], v[70:73]
	v_mfma_f32_16x16x32_bf16 v[66:69], v[184:187], v[228:231], v[66:69]
	s_setprio 0
	s_barrier
	s_add_i32 s75, s75, s53
	v_lshl_add_u64 v[146:147], s[44:45], 0, v[132:133]
	s_mov_b32 m0, s75
	ds_read_b128 v[188:191], v167 offset:16384
	ds_read_b128 v[192:195], v167 offset:17408
	ds_read_b128 v[196:199], v167 offset:18432
	ds_read_b128 v[208:211], v167 offset:19456
	ds_read_b128 v[216:219], v167 offset:20480
	ds_read_b128 v[220:223], v167 offset:21504
	ds_read_b128 v[224:227], v167 offset:22528
	ds_read_b128 v[228:231], v167 offset:23552
	global_load_lds_dwordx4 v[146:147], off
	s_add_i32 m0, s75, 0x2000
	s_add_u32 s76, s44, 0x40000
	v_lshl_add_u64 v[162:163], s[44:45], 0, v[136:137]
	s_addc_u32 s77, s45, 0
	s_add_i32 s43, s43, s53
	global_load_lds_dwordx4 v[162:163], off
	v_lshl_add_u64 v[200:201], s[76:77], 0, v[132:133]
	s_mov_b32 m0, s43
	v_lshl_add_u64 v[204:205], s[46:47], 0, v[134:135]
	global_load_lds_dwordx4 v[200:201], off
	v_lshl_add_u64 v[200:201], s[76:77], 0, v[136:137]
	s_add_i32 m0, s43, 0x2000
	s_nop 0
	global_load_lds_dwordx4 v[200:201], off
	v_lshl_add_u64 v[200:201], s[46:47], 0, v[130:131]
	s_mov_b32 m0, s59
	s_nop 0
	global_load_lds_dwordx4 v[200:201], off
	s_mov_b32 m0, s62
	s_nop 0
	global_load_lds_dwordx4 v[204:205], off
	s_waitcnt vmcnt(8)
	s_waitcnt lgkmcnt(0)
	s_barrier
	s_setprio 1
	s_waitcnt lgkmcnt(0)
	v_mfma_f32_16x16x32_bf16 v[62:65], v[142:145], v[188:191], 0
	v_mfma_f32_16x16x32_bf16 v[58:61], v[158:161], v[188:191], 0
	v_mfma_f32_16x16x32_bf16 v[46:49], v[142:145], v[196:199], 0
	v_mfma_f32_16x16x32_bf16 v[42:45], v[158:161], v[196:199], 0
	v_mfma_f32_16x16x32_bf16 v[28:31], v[142:145], v[216:219], 0
	v_mfma_f32_16x16x32_bf16 v[24:27], v[158:161], v[216:219], 0
	v_mfma_f32_16x16x32_bf16 v[12:15], v[142:145], v[224:227], 0
	v_mfma_f32_16x16x32_bf16 v[8:11], v[158:161], v[224:227], 0
	v_mfma_f32_16x16x32_bf16 v[62:65], v[148:151], v[192:195], v[62:65]
	v_mfma_f32_16x16x32_bf16 v[58:61], v[168:171], v[192:195], v[58:61]
	v_mfma_f32_16x16x32_bf16 v[46:49], v[148:151], v[208:211], v[46:49]
	v_mfma_f32_16x16x32_bf16 v[42:45], v[168:171], v[208:211], v[42:45]
	v_mfma_f32_16x16x32_bf16 v[28:31], v[148:151], v[220:223], v[28:31]
	v_mfma_f32_16x16x32_bf16 v[24:27], v[168:171], v[220:223], v[24:27]
	v_mfma_f32_16x16x32_bf16 v[12:15], v[148:151], v[228:231], v[12:15]
	v_mfma_f32_16x16x32_bf16 v[8:11], v[168:171], v[228:231], v[8:11]
	v_mfma_f32_16x16x32_bf16 v[54:57], v[172:175], v[188:191], 0
	v_mfma_f32_16x16x32_bf16 v[50:53], v[180:183], v[188:191], 0
	v_mfma_f32_16x16x32_bf16 v[38:41], v[172:175], v[196:199], 0
	v_mfma_f32_16x16x32_bf16 v[34:37], v[180:183], v[196:199], 0
	v_mfma_f32_16x16x32_bf16 v[20:23], v[172:175], v[216:219], 0
	v_mfma_f32_16x16x32_bf16 v[16:19], v[180:183], v[216:219], 0
	v_mfma_f32_16x16x32_bf16 v[4:7], v[172:175], v[224:227], 0
	v_mfma_f32_16x16x32_bf16 v[0:3], v[180:183], v[224:227], 0
	v_mfma_f32_16x16x32_bf16 v[54:57], v[176:179], v[192:195], v[54:57]
	v_mfma_f32_16x16x32_bf16 v[50:53], v[184:187], v[192:195], v[50:53]
	v_mfma_f32_16x16x32_bf16 v[38:41], v[176:179], v[208:211], v[38:41]
	v_mfma_f32_16x16x32_bf16 v[34:37], v[184:187], v[208:211], v[34:37]
	v_mfma_f32_16x16x32_bf16 v[20:23], v[176:179], v[220:223], v[20:23]
	v_mfma_f32_16x16x32_bf16 v[16:19], v[184:187], v[220:223], v[16:19]
	v_mfma_f32_16x16x32_bf16 v[4:7], v[176:179], v[228:231], v[4:7]
	v_mfma_f32_16x16x32_bf16 v[0:3], v[184:187], v[228:231], v[0:3]
	s_setprio 0
	s_barrier
	s_branch .Lp3_1829

; #define PG8_STAGE(bufoff, gbase, voff) do { _Pragma("unroll") for (int _i = 0; _i < 2; ++_i) \
;         __builtin_amdgcn_global_load_lds((const unsigned*)((const char*)(gbase) + (voff)[_i]), (PG8_LAS unsigned*)(lds + (bufoff) + ldsw + _i * 8192), 16, 0, 0); } while (0)
; #define PG8_LDA(dst, b, h) do { _Pragma("unroll") for (int m = 0; m < 4; ++m) _Pragma("unroll") for (int k = 0; k < 2; ++k) dst[m][k] = *(const PG8_LAS bf16x8*)(lds + PG8_SA(b, h) + aoff + m * 2048 + k * 1024); } while (0)
; #define PG8_LDB(dst, b, h) do { _Pragma("unroll") for (int n = 0; n < 2; ++n) _Pragma("unroll") for (int k = 0; k < 2; ++k) dst[n][k] = *(const PG8_LAS bf16x8*)(lds + PG8_SB(b, h) + boff + n * 2048 + k * 1024); } while (0)
; #define PG8_WAIT_V(n) asm volatile("s_waitcnt vmcnt(" #n ")" ::: "memory")
; #define PG8_WAIT_L(n) asm volatile("s_waitcnt lgkmcnt(" #n ")" ::: "memory")
; #define PG8_BAR __builtin_amdgcn_s_barrier()
; #define PG8_SCHED __builtin_amdgcn_sched_barrier(0)
; template <class Epi, bool ALIGN_EPI = true>
; __device__ __forceinline__ void gemm_phase(PG8_LAS unsigned char* lds, const Gemm g, const StaticOrder& S, const Epi& E) {
;     ...
;             PG8_LDB(B0, 1, 0); PG8_LDB(B1, 1, 1); PG8_SCHED; PG8_LDA(At, 1, 0); PG8_STAGE(PG8_SA(0, 1), a2 + hstepA, voffA);
;             PG8_WAIT_V(8); PG8_WAIT_L(0); PG8_BAR; PG8_MMA(0, 0, At, B0); PG8_MMA(0, 1, At, B1); PG8_BAR; PG8_SCHED;
.Lp3_1829:
	s_add_i32 s43, 0, 0x18000
	v_add_u32_e32 v32, s43, v165
	s_add_i32 s75, 0, 0x1c000
	ds_read_b128 v[142:145], v32
	ds_read_b128 v[148:151], v32 offset:1024
	ds_read_b128 v[158:161], v32 offset:2048
	ds_read_b128 v[168:171], v32 offset:3072
	v_add_u32_e32 v32, s75, v165
	ds_read_b128 v[172:175], v32
	ds_read_b128 v[176:179], v32 offset:1024
	ds_read_b128 v[180:183], v32 offset:2048
	ds_read_b128 v[184:187], v32 offset:3072
	s_add_u32 s46, s46, 0x40000
	s_addc_u32 s47, s47, 0
	s_mov_b32 m0, s63
	v_lshl_add_u64 v[206:207], s[46:47], 0, v[130:131]
	ds_read_b128 v[188:191], v167 offset:32768
	ds_read_b128 v[192:195], v167 offset:33792
	ds_read_b128 v[196:199], v167 offset:34816
	ds_read_b128 v[208:211], v167 offset:35840
	ds_read_b128 v[216:219], v167 offset:36864
	ds_read_b128 v[220:223], v167 offset:37888
	ds_read_b128 v[224:227], v167 offset:38912
	ds_read_b128 v[228:231], v167 offset:39936
	global_load_lds_dwordx4 v[206:207], off
	v_lshl_add_u64 v[206:207], s[46:47], 0, v[134:135]
	s_mov_b32 m0, s66
	s_nop 0
	global_load_lds_dwordx4 v[206:207], off
	s_waitcnt vmcnt(8)
	s_waitcnt lgkmcnt(0)
	s_barrier
	s_setprio 1
	s_waitcnt lgkmcnt(0)
	v_mfma_f32_16x16x32_bf16 v[126:129], v[142:145], v[188:191], v[126:129]
	v_mfma_f32_16x16x32_bf16 v[122:125], v[158:161], v[188:191], v[122:125]
	v_mfma_f32_16x16x32_bf16 v[110:113], v[142:145], v[196:199], v[110:113]
	v_mfma_f32_16x16x32_bf16 v[106:109], v[158:161], v[196:199], v[106:109]
	v_mfma_f32_16x16x32_bf16 v[94:97], v[142:145], v[216:219], v[94:97]
	v_mfma_f32_16x16x32_bf16 v[90:93], v[158:161], v[216:219], v[90:93]
	v_mfma_f32_16x16x32_bf16 v[78:81], v[142:145], v[224:227], v[78:81]
	v_mfma_f32_16x16x32_bf16 v[74:77], v[158:161], v[224:227], v[74:77]
	v_mfma_f32_16x16x32_bf16 v[126:129], v[148:151], v[192:195], v[126:129]
	v_mfma_f32_16x16x32_bf16 v[122:125], v[168:171], v[192:195], v[122:125]
	v_mfma_f32_16x16x32_bf16 v[110:113], v[148:151], v[208:211], v[110:113]
	v_mfma_f32_16x16x32_bf16 v[106:109], v[168:171], v[208:211], v[106:109]
	v_mfma_f32_16x16x32_bf16 v[94:97], v[148:151], v[220:223], v[94:97]
	v_mfma_f32_16x16x32_bf16 v[90:93], v[168:171], v[220:223], v[90:93]
	v_mfma_f32_16x16x32_bf16 v[78:81], v[148:151], v[228:231], v[78:81]
	v_mfma_f32_16x16x32_bf16 v[74:77], v[168:171], v[228:231], v[74:77]
	v_mfma_f32_16x16x32_bf16 v[118:121], v[172:175], v[188:191], v[118:121]
	v_mfma_f32_16x16x32_bf16 v[114:117], v[180:183], v[188:191], v[114:117]
	v_mfma_f32_16x16x32_bf16 v[102:105], v[172:175], v[196:199], v[102:105]
	v_mfma_f32_16x16x32_bf16 v[98:101], v[180:183], v[196:199], v[98:101]
	v_mfma_f32_16x16x32_bf16 v[86:89], v[172:175], v[216:219], v[86:89]
	v_mfma_f32_16x16x32_bf16 v[82:85], v[180:183], v[216:219], v[82:85]
	v_mfma_f32_16x16x32_bf16 v[70:73], v[172:175], v[224:227], v[70:73]
	v_mfma_f32_16x16x32_bf16 v[66:69], v[180:183], v[224:227], v[66:69]
	v_mfma_f32_16x16x32_bf16 v[118:121], v[176:179], v[192:195], v[118:121]
	v_mfma_f32_16x16x32_bf16 v[114:117], v[184:187], v[192:195], v[114:117]
	v_mfma_f32_16x16x32_bf16 v[102:105], v[176:179], v[208:211], v[102:105]
	v_mfma_f32_16x16x32_bf16 v[98:101], v[184:187], v[208:211], v[98:101]
	v_mfma_f32_16x16x32_bf16 v[86:89], v[176:179], v[220:223], v[86:89]
	v_mfma_f32_16x16x32_bf16 v[82:85], v[184:187], v[220:223], v[82:85]
	v_mfma_f32_16x16x32_bf16 v[70:73], v[176:179], v[228:231], v[70:73]
	v_mfma_f32_16x16x32_bf16 v[66:69], v[184:187], v[228:231], v[66:69]
	s_setprio 0
	s_barrier
; #define PG8_STAGE(bufoff, gbase, voff) do { _Pragma("unroll") for (int _i = 0; _i < 2; ++_i) \
;         __builtin_amdgcn_global_load_lds((const unsigned*)((const char*)(gbase) + (voff)[_i]), (PG8_LAS unsigned*)(lds + (bufoff) + ldsw + _i * 8192), 16, 0, 0); } while (0)
; #define PG8_LDA(dst, b, h) do { _Pragma("unroll") for (int m = 0; m < 4; ++m) _Pragma("unroll") for (int k = 0; k < 2; ++k) dst[m][k] = *(const PG8_LAS bf16x8*)(lds + PG8_SA(b, h) + aoff + m * 2048 + k * 1024); } while (0)
; #define PG8_LDB(dst, b, h) do { _Pragma("unroll") for (int n = 0; n < 2; ++n) _Pragma("unroll") for (int k = 0; k < 2; ++k) dst[n][k] = *(const PG8_LAS bf16x8*)(lds + PG8_SB(b, h) + boff + n * 2048 + k * 1024); } while (0)
; #define PG8_BAR __builtin_amdgcn_s_barrier()
; template <class Epi, bool ALIGN_EPI = true>
; __device__ __forceinline__ void gemm_phase(PG8_LAS unsigned char* lds, const Gemm g, const StaticOrder& S, const Epi& E) {
;     ...
;         for (int t = 0; t < nt; t += 2) {
;             const bool last = (t == nt - 2);
;             const char* a1 = cA + (size_t)(t + 1) * kstep;
;             const char* a2 = last ? nA : cA + (size_t)(t + 2) * kstep; const char* b2 = last ? nB : cB + (size_t)(t + 2) * kstep;
;             const char* a3 = a2 + kstep; const char* b3 = b2 + kstep;
;             PG8_LDB(B0, 0, 0); PG8_LDB(B1, 0, 1); PG8_SCHED; PG8_LDA(At, 0, 0); PG8_STAGE(PG8_SA(1, 1), a1 + hstepA, voffA);
;             PG8_WAIT_V(8); PG8_WAIT_L(0); PG8_BAR; PG8_MMA(0, 0, At, B0); PG8_MMA(0, 1, At, B1); PG8_BAR; PG8_SCHED;
;             PG8_LDA(At, 0, 1); PG8_STAGE(PG8_SB(0, 0), b2, voffB); PG8_STAGE(PG8_SB(0, 1), b2 + hstepB, voffB); PG8_STAGE(PG8_SA(0, 0), a2, voffA);
;             PG8_WAIT_V(8); PG8_WAIT_L(0); PG8_BAR; PG8_MMA(1, 0, At, B0); PG8_MMA(1, 1, At, B1); PG8_BAR; PG8_SCHED;
;             PG8_LDB(B0, 1, 0); PG8_LDB(B1, 1, 1); PG8_SCHED; PG8_LDA(At, 1, 0); PG8_STAGE(PG8_SA(0, 1), a2 + hstepA, voffA);
;             PG8_WAIT_V(8); PG8_WAIT_L(0); PG8_BAR; PG8_MMA(0, 0, At, B0); PG8_MMA(0, 1, At, B1); PG8_BAR; PG8_SCHED;
;             PG8_LDA(At, 1, 1); PG8_STAGE(PG8_SB(1, 0), b3, voffB); PG8_STAGE(PG8_SB(1, 1), b3 + hstepB, voffB); PG8_STAGE(PG8_SA(1, 0), a3, voffA);
;             PG8_WAIT_V(8); PG8_WAIT_L(0); PG8_BAR; PG8_MMA(1, 0, At, B0); PG8_MMA(1, 1, At, B1); PG8_BAR; PG8_SCHED;
;         }
;         if constexpr (ALIGN_EPI) { if (wr == 0) PG8_BAR; }
	s_add_i32 s43, s43, s53
	v_lshl_add_u64 v[146:147], v[146:147], 0, s[60:61]
	s_mov_b32 m0, s43
	ds_read_b128 v[188:191], v167 offset:49152
	ds_read_b128 v[192:195], v167 offset:50176
	ds_read_b128 v[196:199], v167 offset:51200
	ds_read_b128 v[208:211], v167 offset:52224
	ds_read_b128 v[216:219], v167 offset:53248
	ds_read_b128 v[220:223], v167 offset:54272
	ds_read_b128 v[224:227], v167 offset:55296
	ds_read_b128 v[228:231], v167 offset:56320
	global_load_lds_dwordx4 v[146:147], off
	s_add_i32 m0, s43, 0x2000
	s_add_u32 s44, s44, 0x40080
	v_lshl_add_u64 v[146:147], v[162:163], 0, s[60:61]
	s_addc_u32 s45, s45, 0
	s_add_i32 s43, s75, s53
	global_load_lds_dwordx4 v[146:147], off
	v_lshl_add_u64 v[146:147], s[44:45], 0, v[132:133]
	s_mov_b32 m0, s43
	s_nop 0
	global_load_lds_dwordx4 v[146:147], off
	v_lshl_add_u64 v[146:147], s[44:45], 0, v[136:137]
	s_add_i32 m0, s43, 0x2000
	s_nop 0
	global_load_lds_dwordx4 v[146:147], off
	v_lshl_add_u64 v[146:147], v[200:201], 0, s[60:61]
	s_mov_b32 m0, s70
	s_nop 0
	global_load_lds_dwordx4 v[146:147], off
	v_lshl_add_u64 v[146:147], v[204:205], 0, s[60:61]
	s_mov_b32 m0, s71
	s_nop 0
	global_load_lds_dwordx4 v[146:147], off
	s_add_i32 s37, s37, 2
	s_add_u32 s6, s6, 0x100
	s_addc_u32 s7, s7, 0
	s_add_u32 s9, s9, 0x100
	s_addc_u32 s35, s35, 0
	s_add_u32 s43, s6, 0xfffc0080
	s_addc_u32 s44, s7, -1
	s_add_i32 s75, 0, 0x10000
	s_cmp_eq_u32 s37, 12
	s_cselect_b32 s47, s39, s44
	s_cselect_b32 s46, s38, s43
	v_add_u32_e32 v32, s75, v165
	s_cselect_b32 s45, s41, s35
	s_cselect_b32 s44, s40, s9
	s_add_i32 s43, 0, 0x14000
	s_cmp_gt_u32 s37, 13
	s_waitcnt vmcnt(8)
	s_waitcnt lgkmcnt(0)
	s_barrier
	s_setprio 1
	s_waitcnt lgkmcnt(0)
	v_mfma_f32_16x16x32_bf16 v[62:65], v[142:145], v[188:191], v[62:65]
	v_mfma_f32_16x16x32_bf16 v[58:61], v[158:161], v[188:191], v[58:61]
	v_mfma_f32_16x16x32_bf16 v[46:49], v[142:145], v[196:199], v[46:49]
	v_mfma_f32_16x16x32_bf16 v[42:45], v[158:161], v[196:199], v[42:45]
	v_mfma_f32_16x16x32_bf16 v[28:31], v[142:145], v[216:219], v[28:31]
	v_mfma_f32_16x16x32_bf16 v[24:27], v[158:161], v[216:219], v[24:27]
	v_mfma_f32_16x16x32_bf16 v[12:15], v[142:145], v[224:227], v[12:15]
	v_mfma_f32_16x16x32_bf16 v[8:11], v[158:161], v[224:227], v[8:11]
	v_mfma_f32_16x16x32_bf16 v[62:65], v[148:151], v[192:195], v[62:65]
	v_mfma_f32_16x16x32_bf16 v[58:61], v[168:171], v[192:195], v[58:61]
	v_mfma_f32_16x16x32_bf16 v[46:49], v[148:151], v[208:211], v[46:49]
	v_mfma_f32_16x16x32_bf16 v[42:45], v[168:171], v[208:211], v[42:45]
	v_mfma_f32_16x16x32_bf16 v[28:31], v[148:151], v[220:223], v[28:31]
	v_mfma_f32_16x16x32_bf16 v[24:27], v[168:171], v[220:223], v[24:27]
	v_mfma_f32_16x16x32_bf16 v[12:15], v[148:151], v[228:231], v[12:15]
	v_mfma_f32_16x16x32_bf16 v[8:11], v[168:171], v[228:231], v[8:11]
	v_mfma_f32_16x16x32_bf16 v[54:57], v[172:175], v[188:191], v[54:57]
	v_mfma_f32_16x16x32_bf16 v[50:53], v[180:183], v[188:191], v[50:53]
	v_mfma_f32_16x16x32_bf16 v[38:41], v[172:175], v[196:199], v[38:41]
	v_mfma_f32_16x16x32_bf16 v[34:37], v[180:183], v[196:199], v[34:37]
	v_mfma_f32_16x16x32_bf16 v[20:23], v[172:175], v[216:219], v[20:23]
	v_mfma_f32_16x16x32_bf16 v[16:19], v[180:183], v[216:219], v[16:19]
	v_mfma_f32_16x16x32_bf16 v[4:7], v[172:175], v[224:227], v[4:7]
	v_mfma_f32_16x16x32_bf16 v[0:3], v[180:183], v[224:227], v[0:3]
	v_mfma_f32_16x16x32_bf16 v[54:57], v[176:179], v[192:195], v[54:57]
	v_mfma_f32_16x16x32_bf16 v[50:53], v[184:187], v[192:195], v[50:53]
	v_mfma_f32_16x16x32_bf16 v[38:41], v[176:179], v[208:211], v[38:41]
	v_mfma_f32_16x16x32_bf16 v[34:37], v[184:187], v[208:211], v[34:37]
	v_mfma_f32_16x16x32_bf16 v[20:23], v[176:179], v[220:223], v[20:23]
	v_mfma_f32_16x16x32_bf16 v[16:19], v[184:187], v[220:223], v[16:19]
	v_mfma_f32_16x16x32_bf16 v[4:7], v[176:179], v[228:231], v[4:7]
	v_mfma_f32_16x16x32_bf16 v[0:3], v[184:187], v[228:231], v[0:3]
	s_setprio 0
	s_barrier
	s_cbranch_scc0 .Lrot_1829
	s_and_b64 vcc, exec, s[26:27]
	s_cbranch_vccz .LBB0_1832
	s_barrier

; template <class Epi, bool ALIGN_EPI = true>
; __device__ __forceinline__ void gemm_phase(PG8_LAS unsigned char* lds, const Gemm g, const StaticOrder& S, const Epi& E) {
;     ...
;         const bool has_next = S.next(ui + 1, nxt);
;         const char* nA = has_next ? (const char*)g.A + (size_t)nxt.pm * tstepA + (size_t)nxt.ks * ksA : cA; const char* nB = has_next ? (const char*)g.Bt + (size_t)nxt.pn * tstepB + (size_t)nxt.ks * ksA : cB;
;         for (int t = 0; t < nt; t += 2) {
;             const bool last = (t == nt - 2);
;             const char* a1 = cA + (size_t)(t + 1) * kstep;
;             const char* a2 = last ? nA : cA + (size_t)(t + 2) * kstep; const char* b2 = last ? nB : cB + (size_t)(t + 2) * kstep;
;             const char* a3 = a2 + kstep; const char* b3 = b2 + kstep;
.LBB0_2031:
	s_ashr_i32 s29, s28, 31
	s_lshl_b64 s[30:31], s[28:29], 19
	s_add_u32 s30, s49, s30
	s_addc_u32 s31, s50, s31
	s_and_b64 s[34:35], s[2:3], exec
	s_cselect_b32 s29, s31, s41
	s_cselect_b32 s37, s30, s40
	s_ashr_i32 s27, s26, 31
	s_lshl_b64 s[34:35], s[26:27], 19
	s_add_u32 s34, s51, s34
	s_addc_u32 s35, s52, s35
	s_and_b64 s[44:45], s[2:3], exec
	s_cselect_b32 s27, s35, s43
	s_cselect_b32 s82, s34, s42
	s_add_u32 s40, s40, 0x40080
	s_addc_u32 s41, s41, 0
	s_add_u32 s83, s42, 0x100
	s_addc_u32 s85, s43, 0
	s_mov_b32 s86, -2
; #define PG8_STAGE(bufoff, gbase, voff) do { _Pragma("unroll") for (int _i = 0; _i < 2; ++_i) \
;         __builtin_amdgcn_global_load_lds((const unsigned*)((const char*)(gbase) + (voff)[_i]), (PG8_LAS unsigned*)(lds + (bufoff) + ldsw + _i * 8192), 16, 0, 0); } while (0)
; #define PG8_LDA(dst, b, h) do { _Pragma("unroll") for (int m = 0; m < 4; ++m) _Pragma("unroll") for (int k = 0; k < 2; ++k) dst[m][k] = *(const PG8_LAS bf16x8*)(lds + PG8_SA(b, h) + aoff + m * 2048 + k * 1024); } while (0)
; #define PG8_LDB(dst, b, h) do { _Pragma("unroll") for (int n = 0; n < 2; ++n) _Pragma("unroll") for (int k = 0; k < 2; ++k) dst[n][k] = *(const PG8_LAS bf16x8*)(lds + PG8_SB(b, h) + boff + n * 2048 + k * 1024); } while (0)
; #define PG8_WAIT_V(n) asm volatile("s_waitcnt vmcnt(" #n ")" ::: "memory")
; #define PG8_WAIT_L(n) asm volatile("s_waitcnt lgkmcnt(" #n ")" ::: "memory")
; #define PG8_BAR __builtin_amdgcn_s_barrier()
; #define PG8_SCHED __builtin_amdgcn_sched_barrier(0)
; template <class Epi, bool ALIGN_EPI = true>
; __device__ __forceinline__ void gemm_phase(PG8_LAS unsigned char* lds, const Gemm g, const StaticOrder& S, const Epi& E) {
;     ...
;         for (int t = 0; t < nt; t += 2) {
;             const bool last = (t == nt - 2);
;             const char* a1 = cA + (size_t)(t + 1) * kstep;
;             const char* a2 = last ? nA : cA + (size_t)(t + 2) * kstep; const char* b2 = last ? nB : cB + (size_t)(t + 2) * kstep;
;             const char* a3 = a2 + kstep; const char* b3 = b2 + kstep;
;             PG8_LDB(B0, 0, 0); PG8_LDB(B1, 0, 1); PG8_SCHED; PG8_LDA(At, 0, 0); PG8_STAGE(PG8_SA(1, 1), a1 + hstepA, voffA);
;             PG8_WAIT_V(8); PG8_WAIT_L(0); PG8_BAR; PG8_MMA(0, 0, At, B0); PG8_MMA(0, 1, At, B1); PG8_BAR; PG8_SCHED;
;             PG8_LDA(At, 0, 1); PG8_STAGE(PG8_SB(0, 0), b2, voffB); PG8_STAGE(PG8_SB(0, 1), b2 + hstepB, voffB); PG8_STAGE(PG8_SA(0, 0), a2, voffA);
;             PG8_WAIT_V(8); PG8_WAIT_L(0); PG8_BAR; PG8_MMA(1, 0, At, B0); PG8_MMA(1, 1, At, B1); PG8_BAR; PG8_SCHED;
.LBB0_2032:
	s_add_u32 s42, s40, 0xfffc0080
	s_addc_u32 s43, s41, -1
	s_add_i32 s87, 0, 0x10000
	s_cmp_eq_u32 s86, 12
	s_cselect_b32 s45, s29, s43
	s_cselect_b32 s44, s37, s42
	v_add_u32_e32 v144, s87, v159
	s_cselect_b32 s43, s27, s85
	s_cselect_b32 s42, s82, s83
	s_add_i32 s90, 0, 0x14000
	ds_read_b128 v[140:143], v144
	ds_read_b128 v[148:151], v144 offset:1024
	ds_read_b128 v[162:165], v144 offset:2048
	ds_read_b128 v[166:169], v144 offset:3072
	v_add_u32_e32 v144, s90, v159
	ds_read_b128 v[170:173], v144
	ds_read_b128 v[174:177], v144 offset:1024
	ds_read_b128 v[178:181], v144 offset:2048
	ds_read_b128 v[182:185], v144 offset:3072
	v_lshl_add_u64 v[144:145], s[40:41], 0, v[136:137]
	s_add_i32 m0, s39, 0xc000
	ds_read_b128 v[186:189], v161
	ds_read_b128 v[190:193], v161 offset:1024
	ds_read_b128 v[194:197], v161 offset:2048
	ds_read_b128 v[198:201], v161 offset:3072
	ds_read_b128 v[208:211], v161 offset:4096
	ds_read_b128 v[216:219], v161 offset:5120
	ds_read_b128 v[220:223], v161 offset:6144
	ds_read_b128 v[224:227], v161 offset:7168
	global_load_lds_dwordx4 v[144:145], off
	v_lshl_add_u64 v[144:145], s[40:41], 0, v[138:139]
	s_add_i32 m0, s39, 0xe000
	s_nop 0
	global_load_lds_dwordx4 v[144:145], off
	s_waitcnt vmcnt(8)
	s_waitcnt lgkmcnt(0)
	s_barrier
	s_setprio 1
	s_waitcnt lgkmcnt(0)
	v_mfma_f32_16x16x32_bf16 v[126:129], v[140:143], v[186:189], 0
	v_mfma_f32_16x16x32_bf16 v[122:125], v[162:165], v[186:189], 0
	v_mfma_f32_16x16x32_bf16 v[110:113], v[140:143], v[194:197], 0
	v_mfma_f32_16x16x32_bf16 v[106:109], v[162:165], v[194:197], 0
	v_mfma_f32_16x16x32_bf16 v[94:97], v[140:143], v[208:211], 0
	v_mfma_f32_16x16x32_bf16 v[90:93], v[162:165], v[208:211], 0
	v_mfma_f32_16x16x32_bf16 v[78:81], v[140:143], v[220:223], 0
	v_mfma_f32_16x16x32_bf16 v[74:77], v[162:165], v[220:223], 0
	v_mfma_f32_16x16x32_bf16 v[126:129], v[148:151], v[190:193], v[126:129]
	v_mfma_f32_16x16x32_bf16 v[122:125], v[166:169], v[190:193], v[122:125]
	v_mfma_f32_16x16x32_bf16 v[110:113], v[148:151], v[198:201], v[110:113]
	v_mfma_f32_16x16x32_bf16 v[106:109], v[166:169], v[198:201], v[106:109]
	v_mfma_f32_16x16x32_bf16 v[94:97], v[148:151], v[216:219], v[94:97]
	v_mfma_f32_16x16x32_bf16 v[90:93], v[166:169], v[216:219], v[90:93]
	v_mfma_f32_16x16x32_bf16 v[78:81], v[148:151], v[224:227], v[78:81]
	v_mfma_f32_16x16x32_bf16 v[74:77], v[166:169], v[224:227], v[74:77]
	v_mfma_f32_16x16x32_bf16 v[118:121], v[170:173], v[186:189], 0
	v_mfma_f32_16x16x32_bf16 v[114:117], v[178:181], v[186:189], 0
	v_mfma_f32_16x16x32_bf16 v[102:105], v[170:173], v[194:197], 0
	v_mfma_f32_16x16x32_bf16 v[98:101], v[178:181], v[194:197], 0
	v_mfma_f32_16x16x32_bf16 v[86:89], v[170:173], v[208:211], 0
	v_mfma_f32_16x16x32_bf16 v[82:85], v[178:181], v[208:211], 0
	v_mfma_f32_16x16x32_bf16 v[70:73], v[170:173], v[220:223], 0
	v_mfma_f32_16x16x32_bf16 v[66:69], v[178:181], v[220:223], 0
	v_mfma_f32_16x16x32_bf16 v[118:121], v[174:177], v[190:193], v[118:121]
	v_mfma_f32_16x16x32_bf16 v[114:117], v[182:185], v[190:193], v[114:117]
	v_mfma_f32_16x16x32_bf16 v[102:105], v[174:177], v[198:201], v[102:105]
	v_mfma_f32_16x16x32_bf16 v[98:101], v[182:185], v[198:201], v[98:101]
	v_mfma_f32_16x16x32_bf16 v[86:89], v[174:177], v[216:219], v[86:89]
	v_mfma_f32_16x16x32_bf16 v[82:85], v[182:185], v[216:219], v[82:85]
	v_mfma_f32_16x16x32_bf16 v[70:73], v[174:177], v[224:227], v[70:73]
	v_mfma_f32_16x16x32_bf16 v[66:69], v[182:185], v[224:227], v[66:69]
	s_setprio 0
	s_barrier
	s_add_i32 s87, s87, s53
	v_lshl_add_u64 v[144:145], s[42:43], 0, v[32:33]
	s_mov_b32 m0, s87
	ds_read_b128 v[186:189], v161 offset:16384
	ds_read_b128 v[190:193], v161 offset:17408
	ds_read_b128 v[194:197], v161 offset:18432
	ds_read_b128 v[198:201], v161 offset:19456
	ds_read_b128 v[208:211], v161 offset:20480
	ds_read_b128 v[216:219], v161 offset:21504
	ds_read_b128 v[220:223], v161 offset:22528
	ds_read_b128 v[224:227], v161 offset:23552
	global_load_lds_dwordx4 v[144:145], off
	s_add_i32 m0, s87, 0x2000
	s_add_u32 s88, s42, 0x40000
	v_lshl_add_u64 v[146:147], s[42:43], 0, v[134:135]
	s_addc_u32 s89, s43, 0
	s_add_i32 s87, s90, s53
	global_load_lds_dwordx4 v[146:147], off
	v_lshl_add_u64 v[204:205], s[88:89], 0, v[32:33]
	s_mov_b32 m0, s87
	v_lshl_add_u64 v[206:207], s[44:45], 0, v[132:133]
	global_load_lds_dwordx4 v[204:205], off
	v_lshl_add_u64 v[204:205], s[88:89], 0, v[134:135]
	s_add_i32 m0, s87, 0x2000
	s_nop 0
	global_load_lds_dwordx4 v[204:205], off
	v_lshl_add_u64 v[204:205], s[44:45], 0, v[130:131]
	s_mov_b32 m0, s39
	s_nop 0
	global_load_lds_dwordx4 v[204:205], off
	s_mov_b32 m0, s67
	s_nop 0
	global_load_lds_dwordx4 v[206:207], off
	s_waitcnt vmcnt(8)
	s_waitcnt lgkmcnt(0)
	s_barrier
	s_setprio 1
	s_waitcnt lgkmcnt(0)
	v_mfma_f32_16x16x32_bf16 v[62:65], v[140:143], v[186:189], 0
	v_mfma_f32_16x16x32_bf16 v[58:61], v[162:165], v[186:189], 0
	v_mfma_f32_16x16x32_bf16 v[46:49], v[140:143], v[194:197], 0
	v_mfma_f32_16x16x32_bf16 v[42:45], v[162:165], v[194:197], 0
	v_mfma_f32_16x16x32_bf16 v[28:31], v[140:143], v[208:211], 0
	v_mfma_f32_16x16x32_bf16 v[24:27], v[162:165], v[208:211], 0
	v_mfma_f32_16x16x32_bf16 v[12:15], v[140:143], v[220:223], 0
	v_mfma_f32_16x16x32_bf16 v[8:11], v[162:165], v[220:223], 0
	v_mfma_f32_16x16x32_bf16 v[62:65], v[148:151], v[190:193], v[62:65]
	v_mfma_f32_16x16x32_bf16 v[58:61], v[166:169], v[190:193], v[58:61]
	v_mfma_f32_16x16x32_bf16 v[46:49], v[148:151], v[198:201], v[46:49]
	v_mfma_f32_16x16x32_bf16 v[42:45], v[166:169], v[198:201], v[42:45]
	v_mfma_f32_16x16x32_bf16 v[28:31], v[148:151], v[216:219], v[28:31]
	v_mfma_f32_16x16x32_bf16 v[24:27], v[166:169], v[216:219], v[24:27]
	v_mfma_f32_16x16x32_bf16 v[12:15], v[148:151], v[224:227], v[12:15]
	v_mfma_f32_16x16x32_bf16 v[8:11], v[166:169], v[224:227], v[8:11]
	v_mfma_f32_16x16x32_bf16 v[54:57], v[170:173], v[186:189], 0
	v_mfma_f32_16x16x32_bf16 v[50:53], v[178:181], v[186:189], 0
	v_mfma_f32_16x16x32_bf16 v[38:41], v[170:173], v[194:197], 0
	v_mfma_f32_16x16x32_bf16 v[34:37], v[178:181], v[194:197], 0
	v_mfma_f32_16x16x32_bf16 v[20:23], v[170:173], v[208:211], 0
	v_mfma_f32_16x16x32_bf16 v[16:19], v[178:181], v[208:211], 0
	v_mfma_f32_16x16x32_bf16 v[4:7], v[170:173], v[220:223], 0
	v_mfma_f32_16x16x32_bf16 v[0:3], v[178:181], v[220:223], 0
	v_mfma_f32_16x16x32_bf16 v[54:57], v[174:177], v[190:193], v[54:57]
	v_mfma_f32_16x16x32_bf16 v[50:53], v[182:185], v[190:193], v[50:53]
	v_mfma_f32_16x16x32_bf16 v[38:41], v[174:177], v[198:201], v[38:41]
	v_mfma_f32_16x16x32_bf16 v[34:37], v[182:185], v[198:201], v[34:37]
	v_mfma_f32_16x16x32_bf16 v[20:23], v[174:177], v[216:219], v[20:23]
	v_mfma_f32_16x16x32_bf16 v[16:19], v[182:185], v[216:219], v[16:19]
	v_mfma_f32_16x16x32_bf16 v[4:7], v[174:177], v[224:227], v[4:7]
	v_mfma_f32_16x16x32_bf16 v[0:3], v[182:185], v[224:227], v[0:3]
	s_setprio 0
	s_barrier
	s_branch .Lp3_2032

; #define PG8_STAGE(bufoff, gbase, voff) do { _Pragma("unroll") for (int _i = 0; _i < 2; ++_i) \
;         __builtin_amdgcn_global_load_lds((const unsigned*)((const char*)(gbase) + (voff)[_i]), (PG8_LAS unsigned*)(lds + (bufoff) + ldsw + _i * 8192), 16, 0, 0); } while (0)
; #define PG8_LDA(dst, b, h) do { _Pragma("unroll") for (int m = 0; m < 4; ++m) _Pragma("unroll") for (int k = 0; k < 2; ++k) dst[m][k] = *(const PG8_LAS bf16x8*)(lds + PG8_SA(b, h) + aoff + m * 2048 + k * 1024); } while (0)
; #define PG8_LDB(dst, b, h) do { _Pragma("unroll") for (int n = 0; n < 2; ++n) _Pragma("unroll") for (int k = 0; k < 2; ++k) dst[n][k] = *(const PG8_LAS bf16x8*)(lds + PG8_SB(b, h) + boff + n * 2048 + k * 1024); } while (0)
; #define PG8_WAIT_V(n) asm volatile("s_waitcnt vmcnt(" #n ")" ::: "memory")
; #define PG8_WAIT_L(n) asm volatile("s_waitcnt lgkmcnt(" #n ")" ::: "memory")
; #define PG8_BAR __builtin_amdgcn_s_barrier()
; #define PG8_SCHED __builtin_amdgcn_sched_barrier(0)
; template <class Epi, bool ALIGN_EPI = true>
; __device__ __forceinline__ void gemm_phase(PG8_LAS unsigned char* lds, const Gemm g, const StaticOrder& S, const Epi& E) {
;     ...
;             PG8_LDB(B0, 1, 0); PG8_LDB(B1, 1, 1); PG8_SCHED; PG8_LDA(At, 1, 0); PG8_STAGE(PG8_SA(0, 1), a2 + hstepA, voffA);
;             PG8_WAIT_V(8); PG8_WAIT_L(0); PG8_BAR; PG8_MMA(0, 0, At, B0); PG8_MMA(0, 1, At, B1); PG8_BAR; PG8_SCHED;
.Lp3_2032:
	s_add_i32 s87, 0, 0x18000
	v_add_u32_e32 v154, s87, v159
	s_add_i32 s88, 0, 0x1c000
	ds_read_b128 v[140:143], v154
	ds_read_b128 v[148:151], v154 offset:1024
	ds_read_b128 v[162:165], v154 offset:2048
	ds_read_b128 v[166:169], v154 offset:3072
	v_add_u32_e32 v154, s88, v159
	ds_read_b128 v[170:173], v154
	ds_read_b128 v[174:177], v154 offset:1024
	ds_read_b128 v[178:181], v154 offset:2048
	ds_read_b128 v[182:185], v154 offset:3072
	s_add_u32 s44, s44, 0x40000
	s_addc_u32 s45, s45, 0
	s_mov_b32 m0, s70
	v_lshl_add_u64 v[228:229], s[44:45], 0, v[130:131]
	ds_read_b128 v[186:189], v161 offset:32768
	ds_read_b128 v[190:193], v161 offset:33792
	ds_read_b128 v[194:197], v161 offset:34816
	ds_read_b128 v[198:201], v161 offset:35840
	ds_read_b128 v[208:211], v161 offset:36864
	ds_read_b128 v[216:219], v161 offset:37888
	ds_read_b128 v[220:223], v161 offset:38912
	ds_read_b128 v[224:227], v161 offset:39936
	global_load_lds_dwordx4 v[228:229], off
	v_lshl_add_u64 v[228:229], s[44:45], 0, v[132:133]
	s_mov_b32 m0, s71
	s_nop 0
	global_load_lds_dwordx4 v[228:229], off
	s_waitcnt vmcnt(8)
	s_waitcnt lgkmcnt(0)
	s_barrier
	s_setprio 1
	s_waitcnt lgkmcnt(0)
	v_mfma_f32_16x16x32_bf16 v[126:129], v[140:143], v[186:189], v[126:129]
	v_mfma_f32_16x16x32_bf16 v[122:125], v[162:165], v[186:189], v[122:125]
	v_mfma_f32_16x16x32_bf16 v[110:113], v[140:143], v[194:197], v[110:113]
	v_mfma_f32_16x16x32_bf16 v[106:109], v[162:165], v[194:197], v[106:109]
	v_mfma_f32_16x16x32_bf16 v[94:97], v[140:143], v[208:211], v[94:97]
	v_mfma_f32_16x16x32_bf16 v[90:93], v[162:165], v[208:211], v[90:93]
	v_mfma_f32_16x16x32_bf16 v[78:81], v[140:143], v[220:223], v[78:81]
	v_mfma_f32_16x16x32_bf16 v[74:77], v[162:165], v[220:223], v[74:77]
	v_mfma_f32_16x16x32_bf16 v[126:129], v[148:151], v[190:193], v[126:129]
	v_mfma_f32_16x16x32_bf16 v[122:125], v[166:169], v[190:193], v[122:125]
	v_mfma_f32_16x16x32_bf16 v[110:113], v[148:151], v[198:201], v[110:113]
	v_mfma_f32_16x16x32_bf16 v[106:109], v[166:169], v[198:201], v[106:109]
	v_mfma_f32_16x16x32_bf16 v[94:97], v[148:151], v[216:219], v[94:97]
	v_mfma_f32_16x16x32_bf16 v[90:93], v[166:169], v[216:219], v[90:93]
	v_mfma_f32_16x16x32_bf16 v[78:81], v[148:151], v[224:227], v[78:81]
	v_mfma_f32_16x16x32_bf16 v[74:77], v[166:169], v[224:227], v[74:77]
	v_mfma_f32_16x16x32_bf16 v[118:121], v[170:173], v[186:189], v[118:121]
	v_mfma_f32_16x16x32_bf16 v[114:117], v[178:181], v[186:189], v[114:117]
	v_mfma_f32_16x16x32_bf16 v[102:105], v[170:173], v[194:197], v[102:105]
	v_mfma_f32_16x16x32_bf16 v[98:101], v[178:181], v[194:197], v[98:101]
	v_mfma_f32_16x16x32_bf16 v[86:89], v[170:173], v[208:211], v[86:89]
	v_mfma_f32_16x16x32_bf16 v[82:85], v[178:181], v[208:211], v[82:85]
	v_mfma_f32_16x16x32_bf16 v[70:73], v[170:173], v[220:223], v[70:73]
	v_mfma_f32_16x16x32_bf16 v[66:69], v[178:181], v[220:223], v[66:69]
	v_mfma_f32_16x16x32_bf16 v[118:121], v[174:177], v[190:193], v[118:121]
	v_mfma_f32_16x16x32_bf16 v[114:117], v[182:185], v[190:193], v[114:117]
	v_mfma_f32_16x16x32_bf16 v[102:105], v[174:177], v[198:201], v[102:105]
	v_mfma_f32_16x16x32_bf16 v[98:101], v[182:185], v[198:201], v[98:101]
	v_mfma_f32_16x16x32_bf16 v[86:89], v[174:177], v[216:219], v[86:89]
	v_mfma_f32_16x16x32_bf16 v[82:85], v[182:185], v[216:219], v[82:85]
	v_mfma_f32_16x16x32_bf16 v[70:73], v[174:177], v[224:227], v[70:73]
	v_mfma_f32_16x16x32_bf16 v[66:69], v[182:185], v[224:227], v[66:69]
	s_setprio 0
	s_barrier
; #define PG8_STAGE(bufoff, gbase, voff) do { _Pragma("unroll") for (int _i = 0; _i < 2; ++_i) \
;         __builtin_amdgcn_global_load_lds((const unsigned*)((const char*)(gbase) + (voff)[_i]), (PG8_LAS unsigned*)(lds + (bufoff) + ldsw + _i * 8192), 16, 0, 0); } while (0)
; #define PG8_LDA(dst, b, h) do { _Pragma("unroll") for (int m = 0; m < 4; ++m) _Pragma("unroll") for (int k = 0; k < 2; ++k) dst[m][k] = *(const PG8_LAS bf16x8*)(lds + PG8_SA(b, h) + aoff + m * 2048 + k * 1024); } while (0)
; #define PG8_LDB(dst, b, h) do { _Pragma("unroll") for (int n = 0; n < 2; ++n) _Pragma("unroll") for (int k = 0; k < 2; ++k) dst[n][k] = *(const PG8_LAS bf16x8*)(lds + PG8_SB(b, h) + boff + n * 2048 + k * 1024); } while (0)
; #define PG8_BAR __builtin_amdgcn_s_barrier()
; template <class Epi, bool ALIGN_EPI = true>
; __device__ __forceinline__ void gemm_phase(PG8_LAS unsigned char* lds, const Gemm g, const StaticOrder& S, const Epi& E) {
;     ...
;         for (int t = 0; t < nt; t += 2) {
;             const bool last = (t == nt - 2);
;             const char* a1 = cA + (size_t)(t + 1) * kstep;
;             const char* a2 = last ? nA : cA + (size_t)(t + 2) * kstep; const char* b2 = last ? nB : cB + (size_t)(t + 2) * kstep;
;             const char* a3 = a2 + kstep; const char* b3 = b2 + kstep;
;             PG8_LDB(B0, 0, 0); PG8_LDB(B1, 0, 1); PG8_SCHED; PG8_LDA(At, 0, 0); PG8_STAGE(PG8_SA(1, 1), a1 + hstepA, voffA);
;             PG8_WAIT_V(8); PG8_WAIT_L(0); PG8_BAR; PG8_MMA(0, 0, At, B0); PG8_MMA(0, 1, At, B1); PG8_BAR; PG8_SCHED;
;             PG8_LDA(At, 0, 1); PG8_STAGE(PG8_SB(0, 0), b2, voffB); PG8_STAGE(PG8_SB(0, 1), b2 + hstepB, voffB); PG8_STAGE(PG8_SA(0, 0), a2, voffA);
;             PG8_WAIT_V(8); PG8_WAIT_L(0); PG8_BAR; PG8_MMA(1, 0, At, B0); PG8_MMA(1, 1, At, B1); PG8_BAR; PG8_SCHED;
;             PG8_LDB(B0, 1, 0); PG8_LDB(B1, 1, 1); PG8_SCHED; PG8_LDA(At, 1, 0); PG8_STAGE(PG8_SA(0, 1), a2 + hstepA, voffA);
;             PG8_WAIT_V(8); PG8_WAIT_L(0); PG8_BAR; PG8_MMA(0, 0, At, B0); PG8_MMA(0, 1, At, B1); PG8_BAR; PG8_SCHED;
;             PG8_LDA(At, 1, 1); PG8_STAGE(PG8_SB(1, 0), b3, voffB); PG8_STAGE(PG8_SB(1, 1), b3 + hstepB, voffB); PG8_STAGE(PG8_SA(1, 0), a3, voffA);
;             PG8_WAIT_V(8); PG8_WAIT_L(0); PG8_BAR; PG8_MMA(1, 0, At, B0); PG8_MMA(1, 1, At, B1); PG8_BAR; PG8_SCHED;
;         }
;         if constexpr (ALIGN_EPI) { if (wr == 0) PG8_BAR; }
	s_add_i32 s44, s87, s53
	v_lshl_add_u64 v[144:145], v[144:145], 0, s[60:61]
	s_mov_b32 m0, s44
	ds_read_b128 v[186:189], v161 offset:49152
	ds_read_b128 v[190:193], v161 offset:50176
	ds_read_b128 v[194:197], v161 offset:51200
	ds_read_b128 v[198:201], v161 offset:52224
	ds_read_b128 v[208:211], v161 offset:53248
	ds_read_b128 v[216:219], v161 offset:54272
	ds_read_b128 v[220:223], v161 offset:55296
	ds_read_b128 v[224:227], v161 offset:56320
	global_load_lds_dwordx4 v[144:145], off
	s_add_i32 m0, s44, 0x2000
	s_add_u32 s42, s42, 0x40080
	v_lshl_add_u64 v[144:145], v[146:147], 0, s[60:61]
	s_addc_u32 s43, s43, 0
	s_add_i32 s44, s88, s53
	global_load_lds_dwordx4 v[144:145], off
	v_lshl_add_u64 v[144:145], s[42:43], 0, v[32:33]
	s_mov_b32 m0, s44
	s_nop 0
	global_load_lds_dwordx4 v[144:145], off
	v_lshl_add_u64 v[144:145], s[42:43], 0, v[134:135]
	s_add_i32 m0, s44, 0x2000
	s_nop 0
	global_load_lds_dwordx4 v[144:145], off
	v_lshl_add_u64 v[144:145], v[204:205], 0, s[60:61]
	s_mov_b32 m0, s72
	s_nop 0
	global_load_lds_dwordx4 v[144:145], off
	v_lshl_add_u64 v[144:145], v[206:207], 0, s[60:61]
	s_mov_b32 m0, s73
	s_nop 0
	global_load_lds_dwordx4 v[144:145], off
	s_add_i32 s86, s86, 2
	s_add_u32 s40, s40, 0x100
	s_addc_u32 s41, s41, 0
	s_add_u32 s83, s83, 0x100
	s_addc_u32 s85, s85, 0
	s_add_u32 s42, s40, 0xfffc0080
	s_addc_u32 s43, s41, -1
	s_add_i32 s87, 0, 0x10000
	s_cmp_eq_u32 s86, 12
	s_cselect_b32 s45, s29, s43
	s_cselect_b32 s44, s37, s42
	v_add_u32_e32 v144, s87, v159
	s_cselect_b32 s43, s27, s85
	s_cselect_b32 s42, s82, s83
	s_add_i32 s90, 0, 0x14000
	s_cmp_gt_u32 s86, 13
	s_waitcnt vmcnt(8)
	s_waitcnt lgkmcnt(0)
	s_barrier
	s_setprio 1
	s_waitcnt lgkmcnt(0)
	v_mfma_f32_16x16x32_bf16 v[62:65], v[140:143], v[186:189], v[62:65]
	v_mfma_f32_16x16x32_bf16 v[58:61], v[162:165], v[186:189], v[58:61]
	v_mfma_f32_16x16x32_bf16 v[46:49], v[140:143], v[194:197], v[46:49]
	v_mfma_f32_16x16x32_bf16 v[42:45], v[162:165], v[194:197], v[42:45]
	v_mfma_f32_16x16x32_bf16 v[28:31], v[140:143], v[208:211], v[28:31]
	v_mfma_f32_16x16x32_bf16 v[24:27], v[162:165], v[208:211], v[24:27]
	v_mfma_f32_16x16x32_bf16 v[12:15], v[140:143], v[220:223], v[12:15]
	v_mfma_f32_16x16x32_bf16 v[8:11], v[162:165], v[220:223], v[8:11]
	v_mfma_f32_16x16x32_bf16 v[62:65], v[148:151], v[190:193], v[62:65]
	v_mfma_f32_16x16x32_bf16 v[58:61], v[166:169], v[190:193], v[58:61]
	v_mfma_f32_16x16x32_bf16 v[46:49], v[148:151], v[198:201], v[46:49]
	v_mfma_f32_16x16x32_bf16 v[42:45], v[166:169], v[198:201], v[42:45]
	v_mfma_f32_16x16x32_bf16 v[28:31], v[148:151], v[216:219], v[28:31]
	v_mfma_f32_16x16x32_bf16 v[24:27], v[166:169], v[216:219], v[24:27]
	v_mfma_f32_16x16x32_bf16 v[12:15], v[148:151], v[224:227], v[12:15]
	v_mfma_f32_16x16x32_bf16 v[8:11], v[166:169], v[224:227], v[8:11]
	v_mfma_f32_16x16x32_bf16 v[54:57], v[170:173], v[186:189], v[54:57]
	v_mfma_f32_16x16x32_bf16 v[50:53], v[178:181], v[186:189], v[50:53]
	v_mfma_f32_16x16x32_bf16 v[38:41], v[170:173], v[194:197], v[38:41]
	v_mfma_f32_16x16x32_bf16 v[34:37], v[178:181], v[194:197], v[34:37]
	v_mfma_f32_16x16x32_bf16 v[20:23], v[170:173], v[208:211], v[20:23]
	v_mfma_f32_16x16x32_bf16 v[16:19], v[178:181], v[208:211], v[16:19]
	v_mfma_f32_16x16x32_bf16 v[4:7], v[170:173], v[220:223], v[4:7]
	v_mfma_f32_16x16x32_bf16 v[0:3], v[178:181], v[220:223], v[0:3]
	v_mfma_f32_16x16x32_bf16 v[54:57], v[174:177], v[190:193], v[54:57]
	v_mfma_f32_16x16x32_bf16 v[50:53], v[182:185], v[190:193], v[50:53]
	v_mfma_f32_16x16x32_bf16 v[38:41], v[174:177], v[198:201], v[38:41]
	v_mfma_f32_16x16x32_bf16 v[34:37], v[182:185], v[198:201], v[34:37]
	v_mfma_f32_16x16x32_bf16 v[20:23], v[174:177], v[216:219], v[20:23]
	v_mfma_f32_16x16x32_bf16 v[16:19], v[182:185], v[216:219], v[16:19]
	v_mfma_f32_16x16x32_bf16 v[4:7], v[174:177], v[224:227], v[4:7]
	v_mfma_f32_16x16x32_bf16 v[0:3], v[182:185], v[224:227], v[0:3]
	s_setprio 0
	s_barrier
	s_cbranch_scc0 .Lrot_2032
	s_and_b64 vcc, exec, s[14:15]
	s_cbranch_vccz .LBB0_2035
	s_barrier

; template <class Epi, bool ALIGN_EPI = true>
; __device__ __forceinline__ void gemm_phase(PG8_LAS unsigned char* lds, const Gemm g, const StaticOrder& S, const Epi& E) {
;     ...
;         const bool has_next = S.next(ui + 1, nxt);
;         const char* nA = has_next ? (const char*)g.A + (size_t)nxt.pm * tstepA + (size_t)nxt.ks * ksA : cA; const char* nB = has_next ? (const char*)g.Bt + (size_t)nxt.pn * tstepB + (size_t)nxt.ks * ksA : cB;
;         for (int t = 0; t < nt; t += 2) {
;             const bool last = (t == nt - 2);
;             const char* a1 = cA + (size_t)(t + 1) * kstep;
;             const char* a2 = last ? nA : cA + (size_t)(t + 2) * kstep; const char* b2 = last ? nB : cB + (size_t)(t + 2) * kstep;
;             const char* a3 = a2 + kstep; const char* b3 = b2 + kstep;
.LBB0_2131:
	s_ashr_i32 s43, s42, 31
	s_lshl_b64 s[44:45], s[42:43], 21
	s_add_u32 s7, s70, s44
	s_addc_u32 s9, s71, s45
	s_and_b64 s[44:45], s[4:5], exec
	s_cselect_b32 s45, s9, s49
	s_cselect_b32 s44, s7, s48
	s_ashr_i32 s41, s40, 31
	s_lshl_b64 s[46:47], s[40:41], 21
	s_add_u32 s7, s72, s46
	s_addc_u32 s9, s73, s47
	s_and_b64 s[46:47], s[4:5], exec
	s_cselect_b32 s47, s9, s51
	s_cselect_b32 s46, s7, s50
	s_add_u32 s48, s48, 0x100080
	s_addc_u32 s49, s49, 0
	s_add_u32 s7, s50, 0x100
	s_addc_u32 s9, s51, 0
	s_mov_b32 s41, -2
; #define PG8_STAGE(bufoff, gbase, voff) do { _Pragma("unroll") for (int _i = 0; _i < 2; ++_i) \
;         __builtin_amdgcn_global_load_lds((const unsigned*)((const char*)(gbase) + (voff)[_i]), (PG8_LAS unsigned*)(lds + (bufoff) + ldsw + _i * 8192), 16, 0, 0); } while (0)
; #define PG8_LDA(dst, b, h) do { _Pragma("unroll") for (int m = 0; m < 4; ++m) _Pragma("unroll") for (int k = 0; k < 2; ++k) dst[m][k] = *(const PG8_LAS bf16x8*)(lds + PG8_SA(b, h) + aoff + m * 2048 + k * 1024); } while (0)
; #define PG8_LDB(dst, b, h) do { _Pragma("unroll") for (int n = 0; n < 2; ++n) _Pragma("unroll") for (int k = 0; k < 2; ++k) dst[n][k] = *(const PG8_LAS bf16x8*)(lds + PG8_SB(b, h) + boff + n * 2048 + k * 1024); } while (0)
; #define PG8_WAIT_V(n) asm volatile("s_waitcnt vmcnt(" #n ")" ::: "memory")
; #define PG8_WAIT_L(n) asm volatile("s_waitcnt lgkmcnt(" #n ")" ::: "memory")
; #define PG8_BAR __builtin_amdgcn_s_barrier()
; #define PG8_SCHED __builtin_amdgcn_sched_barrier(0)
; template <class Epi, bool ALIGN_EPI = true>
; __device__ __forceinline__ void gemm_phase(PG8_LAS unsigned char* lds, const Gemm g, const StaticOrder& S, const Epi& E) {
;     ...
;             PG8_LDB(B0, 0, 0); PG8_LDB(B1, 0, 1); PG8_SCHED; PG8_LDA(At, 0, 0); PG8_STAGE(PG8_SA(1, 1), a1 + hstepA, voffA);
;             PG8_WAIT_V(8); PG8_WAIT_L(0); PG8_BAR; PG8_MMA(0, 0, At, B0); PG8_MMA(0, 1, At, B1); PG8_BAR; PG8_SCHED;
;             PG8_LDA(At, 0, 1); PG8_STAGE(PG8_SB(0, 0), b2, voffB); PG8_STAGE(PG8_SB(0, 1), b2 + hstepB, voffB); PG8_STAGE(PG8_SA(0, 0), a2, voffA);
;             PG8_WAIT_V(8); PG8_WAIT_L(0); PG8_BAR; PG8_MMA(1, 0, At, B0); PG8_MMA(1, 1, At, B1); PG8_BAR; PG8_SCHED;
;     ...
; #pragma unroll
;         for (int a = 0; a < 2; ++a)
; #pragma unroll
;             for (int b = 0; b < 2; ++b)
; #pragma unroll
;                 for (int m = 0; m < 4; ++m)
; #pragma unroll
;                     for (int n = 0; n < 2; ++n) acc[a][b][m][n] = (f32x4){0.f, 0.f, 0.f, 0.f};
.LBB0_2132:
	s_add_u32 s43, s48, 0xfff00080
	s_addc_u32 s50, s49, -1
	s_add_i32 s93, 0, 0x10000
	s_cmp_eq_u32 s41, 60
	s_cselect_b32 s53, s45, s50
	s_cselect_b32 s52, s44, s43
	v_add_u32_e32 v32, s93, v165
	s_cselect_b32 s51, s47, s9
	s_cselect_b32 s50, s46, s7
	s_add_i32 s43, 0, 0x14000
	ds_read_b128 v[142:145], v32
	ds_read_b128 v[148:151], v32 offset:1024
	ds_read_b128 v[158:161], v32 offset:2048
	ds_read_b128 v[168:171], v32 offset:3072
	v_add_u32_e32 v32, s43, v165
	ds_read_b128 v[172:175], v32
	ds_read_b128 v[176:179], v32 offset:1024
	ds_read_b128 v[180:183], v32 offset:2048
	ds_read_b128 v[184:187], v32 offset:3072
	v_lshl_add_u64 v[146:147], s[48:49], 0, v[138:139]
	s_add_i32 m0, s75, 0xc000
	ds_read_b128 v[188:191], v167
	ds_read_b128 v[192:195], v167 offset:1024
	ds_read_b128 v[196:199], v167 offset:2048
	ds_read_b128 v[208:211], v167 offset:3072
	ds_read_b128 v[216:219], v167 offset:4096
	ds_read_b128 v[220:223], v167 offset:5120
	ds_read_b128 v[224:227], v167 offset:6144
	ds_read_b128 v[228:231], v167 offset:7168
	global_load_lds_dwordx4 v[146:147], off
	v_lshl_add_u64 v[146:147], s[48:49], 0, v[140:141]
	s_add_i32 m0, s75, 0xe000
	s_nop 0
	global_load_lds_dwordx4 v[146:147], off
	s_waitcnt vmcnt(8)
	s_waitcnt lgkmcnt(0)
	s_barrier
	s_setprio 1
	s_waitcnt lgkmcnt(0)
	v_mfma_f32_16x16x32_bf16 v[126:129], v[142:145], v[188:191], 0
	v_mfma_f32_16x16x32_bf16 v[122:125], v[158:161], v[188:191], 0
	v_mfma_f32_16x16x32_bf16 v[110:113], v[142:145], v[196:199], 0
	v_mfma_f32_16x16x32_bf16 v[106:109], v[158:161], v[196:199], 0
	v_mfma_f32_16x16x32_bf16 v[94:97], v[142:145], v[216:219], 0
	v_mfma_f32_16x16x32_bf16 v[90:93], v[158:161], v[216:219], 0
	v_mfma_f32_16x16x32_bf16 v[78:81], v[142:145], v[224:227], 0
	v_mfma_f32_16x16x32_bf16 v[74:77], v[158:161], v[224:227], 0
	v_mfma_f32_16x16x32_bf16 v[126:129], v[148:151], v[192:195], v[126:129]
	v_mfma_f32_16x16x32_bf16 v[122:125], v[168:171], v[192:195], v[122:125]
	v_mfma_f32_16x16x32_bf16 v[110:113], v[148:151], v[208:211], v[110:113]
	v_mfma_f32_16x16x32_bf16 v[106:109], v[168:171], v[208:211], v[106:109]
	v_mfma_f32_16x16x32_bf16 v[94:97], v[148:151], v[220:223], v[94:97]
	v_mfma_f32_16x16x32_bf16 v[90:93], v[168:171], v[220:223], v[90:93]
	v_mfma_f32_16x16x32_bf16 v[78:81], v[148:151], v[228:231], v[78:81]
	v_mfma_f32_16x16x32_bf16 v[74:77], v[168:171], v[228:231], v[74:77]
	v_mfma_f32_16x16x32_bf16 v[118:121], v[172:175], v[188:191], 0
	v_mfma_f32_16x16x32_bf16 v[114:117], v[180:183], v[188:191], 0
	v_mfma_f32_16x16x32_bf16 v[102:105], v[172:175], v[196:199], 0
	v_mfma_f32_16x16x32_bf16 v[98:101], v[180:183], v[196:199], 0
	v_mfma_f32_16x16x32_bf16 v[86:89], v[172:175], v[216:219], 0
	v_mfma_f32_16x16x32_bf16 v[82:85], v[180:183], v[216:219], 0
	v_mfma_f32_16x16x32_bf16 v[70:73], v[172:175], v[224:227], 0
	v_mfma_f32_16x16x32_bf16 v[66:69], v[180:183], v[224:227], 0
	v_mfma_f32_16x16x32_bf16 v[118:121], v[176:179], v[192:195], v[118:121]
	v_mfma_f32_16x16x32_bf16 v[114:117], v[184:187], v[192:195], v[114:117]
	v_mfma_f32_16x16x32_bf16 v[102:105], v[176:179], v[208:211], v[102:105]
	v_mfma_f32_16x16x32_bf16 v[98:101], v[184:187], v[208:211], v[98:101]
	v_mfma_f32_16x16x32_bf16 v[86:89], v[176:179], v[220:223], v[86:89]
	v_mfma_f32_16x16x32_bf16 v[82:85], v[184:187], v[220:223], v[82:85]
	v_mfma_f32_16x16x32_bf16 v[70:73], v[176:179], v[228:231], v[70:73]
	v_mfma_f32_16x16x32_bf16 v[66:69], v[184:187], v[228:231], v[66:69]
	s_setprio 0
	s_barrier
	s_add_i32 s93, s93, s74
	v_lshl_add_u64 v[146:147], s[50:51], 0, v[132:133]
	s_mov_b32 m0, s93
	ds_read_b128 v[188:191], v167 offset:16384
	ds_read_b128 v[192:195], v167 offset:17408
	ds_read_b128 v[196:199], v167 offset:18432
	ds_read_b128 v[208:211], v167 offset:19456
	ds_read_b128 v[216:219], v167 offset:20480
	ds_read_b128 v[220:223], v167 offset:21504
	ds_read_b128 v[224:227], v167 offset:22528
	ds_read_b128 v[228:231], v167 offset:23552
	global_load_lds_dwordx4 v[146:147], off
	s_add_i32 m0, s93, 0x2000
	s_add_u32 s94, s50, 0x100000
	v_lshl_add_u64 v[162:163], s[50:51], 0, v[136:137]
	s_addc_u32 s95, s51, 0
	s_add_i32 s43, s43, s74
	global_load_lds_dwordx4 v[162:163], off
	v_lshl_add_u64 v[200:201], s[94:95], 0, v[132:133]
	s_mov_b32 m0, s43
	v_lshl_add_u64 v[204:205], s[52:53], 0, v[134:135]
	global_load_lds_dwordx4 v[200:201], off
	v_lshl_add_u64 v[200:201], s[94:95], 0, v[136:137]
	s_add_i32 m0, s43, 0x2000
	s_nop 0
	global_load_lds_dwordx4 v[200:201], off
	v_lshl_add_u64 v[200:201], s[52:53], 0, v[130:131]
	s_mov_b32 m0, s75
	s_nop 0
	global_load_lds_dwordx4 v[200:201], off
	s_mov_b32 m0, s76
	s_nop 0
	global_load_lds_dwordx4 v[204:205], off
	s_waitcnt vmcnt(8)
	s_waitcnt lgkmcnt(0)
	s_barrier
	s_setprio 1
	s_waitcnt lgkmcnt(0)
	v_mfma_f32_16x16x32_bf16 v[62:65], v[142:145], v[188:191], 0
	v_mfma_f32_16x16x32_bf16 v[58:61], v[158:161], v[188:191], 0
	v_mfma_f32_16x16x32_bf16 v[46:49], v[142:145], v[196:199], 0
	v_mfma_f32_16x16x32_bf16 v[42:45], v[158:161], v[196:199], 0
	v_mfma_f32_16x16x32_bf16 v[28:31], v[142:145], v[216:219], 0
	v_mfma_f32_16x16x32_bf16 v[24:27], v[158:161], v[216:219], 0
	v_mfma_f32_16x16x32_bf16 v[12:15], v[142:145], v[224:227], 0
	v_mfma_f32_16x16x32_bf16 v[8:11], v[158:161], v[224:227], 0
	v_mfma_f32_16x16x32_bf16 v[62:65], v[148:151], v[192:195], v[62:65]
	v_mfma_f32_16x16x32_bf16 v[58:61], v[168:171], v[192:195], v[58:61]
	v_mfma_f32_16x16x32_bf16 v[46:49], v[148:151], v[208:211], v[46:49]
	v_mfma_f32_16x16x32_bf16 v[42:45], v[168:171], v[208:211], v[42:45]
	v_mfma_f32_16x16x32_bf16 v[28:31], v[148:151], v[220:223], v[28:31]
	v_mfma_f32_16x16x32_bf16 v[24:27], v[168:171], v[220:223], v[24:27]
	v_mfma_f32_16x16x32_bf16 v[12:15], v[148:151], v[228:231], v[12:15]
	v_mfma_f32_16x16x32_bf16 v[8:11], v[168:171], v[228:231], v[8:11]
	v_mfma_f32_16x16x32_bf16 v[54:57], v[172:175], v[188:191], 0
	v_mfma_f32_16x16x32_bf16 v[50:53], v[180:183], v[188:191], 0
	v_mfma_f32_16x16x32_bf16 v[38:41], v[172:175], v[196:199], 0
	v_mfma_f32_16x16x32_bf16 v[34:37], v[180:183], v[196:199], 0
	v_mfma_f32_16x16x32_bf16 v[20:23], v[172:175], v[216:219], 0
	v_mfma_f32_16x16x32_bf16 v[16:19], v[180:183], v[216:219], 0
	v_mfma_f32_16x16x32_bf16 v[4:7], v[172:175], v[224:227], 0
	v_mfma_f32_16x16x32_bf16 v[0:3], v[180:183], v[224:227], 0
	v_mfma_f32_16x16x32_bf16 v[54:57], v[176:179], v[192:195], v[54:57]
	v_mfma_f32_16x16x32_bf16 v[50:53], v[184:187], v[192:195], v[50:53]
	v_mfma_f32_16x16x32_bf16 v[38:41], v[176:179], v[208:211], v[38:41]
	v_mfma_f32_16x16x32_bf16 v[34:37], v[184:187], v[208:211], v[34:37]
	v_mfma_f32_16x16x32_bf16 v[20:23], v[176:179], v[220:223], v[20:23]
	v_mfma_f32_16x16x32_bf16 v[16:19], v[184:187], v[220:223], v[16:19]
	v_mfma_f32_16x16x32_bf16 v[4:7], v[176:179], v[228:231], v[4:7]
	v_mfma_f32_16x16x32_bf16 v[0:3], v[184:187], v[228:231], v[0:3]
	s_setprio 0
	s_barrier
	s_branch .Lp3_2132

; #define PG8_STAGE(bufoff, gbase, voff) do { _Pragma("unroll") for (int _i = 0; _i < 2; ++_i) \
;         __builtin_amdgcn_global_load_lds((const unsigned*)((const char*)(gbase) + (voff)[_i]), (PG8_LAS unsigned*)(lds + (bufoff) + ldsw + _i * 8192), 16, 0, 0); } while (0)
; #define PG8_LDA(dst, b, h) do { _Pragma("unroll") for (int m = 0; m < 4; ++m) _Pragma("unroll") for (int k = 0; k < 2; ++k) dst[m][k] = *(const PG8_LAS bf16x8*)(lds + PG8_SA(b, h) + aoff + m * 2048 + k * 1024); } while (0)
; #define PG8_LDB(dst, b, h) do { _Pragma("unroll") for (int n = 0; n < 2; ++n) _Pragma("unroll") for (int k = 0; k < 2; ++k) dst[n][k] = *(const PG8_LAS bf16x8*)(lds + PG8_SB(b, h) + boff + n * 2048 + k * 1024); } while (0)
; #define PG8_WAIT_V(n) asm volatile("s_waitcnt vmcnt(" #n ")" ::: "memory")
; #define PG8_WAIT_L(n) asm volatile("s_waitcnt lgkmcnt(" #n ")" ::: "memory")
; #define PG8_BAR __builtin_amdgcn_s_barrier()
; #define PG8_SCHED __builtin_amdgcn_sched_barrier(0)
; template <class Epi, bool ALIGN_EPI = true>
; __device__ __forceinline__ void gemm_phase(PG8_LAS unsigned char* lds, const Gemm g, const StaticOrder& S, const Epi& E) {
;     ...
;             PG8_LDB(B0, 1, 0); PG8_LDB(B1, 1, 1); PG8_SCHED; PG8_LDA(At, 1, 0); PG8_STAGE(PG8_SA(0, 1), a2 + hstepA, voffA);
;             PG8_WAIT_V(8); PG8_WAIT_L(0); PG8_BAR; PG8_MMA(0, 0, At, B0); PG8_MMA(0, 1, At, B1); PG8_BAR; PG8_SCHED;
.Lp3_2132:
	s_add_i32 s43, 0, 0x18000
	v_add_u32_e32 v32, s43, v165
	s_add_i32 s93, 0, 0x1c000
	ds_read_b128 v[142:145], v32
	ds_read_b128 v[148:151], v32 offset:1024
	ds_read_b128 v[158:161], v32 offset:2048
	ds_read_b128 v[168:171], v32 offset:3072
	v_add_u32_e32 v32, s93, v165
	ds_read_b128 v[172:175], v32
	ds_read_b128 v[176:179], v32 offset:1024
	ds_read_b128 v[180:183], v32 offset:2048
	ds_read_b128 v[184:187], v32 offset:3072
	s_add_u32 s52, s52, 0x100000
	s_addc_u32 s53, s53, 0
	s_mov_b32 m0, s77
	v_lshl_add_u64 v[206:207], s[52:53], 0, v[130:131]
	ds_read_b128 v[188:191], v167 offset:32768
	ds_read_b128 v[192:195], v167 offset:33792
	ds_read_b128 v[196:199], v167 offset:34816
	ds_read_b128 v[208:211], v167 offset:35840
	ds_read_b128 v[216:219], v167 offset:36864
	ds_read_b128 v[220:223], v167 offset:37888
	ds_read_b128 v[224:227], v167 offset:38912
	ds_read_b128 v[228:231], v167 offset:39936
	global_load_lds_dwordx4 v[206:207], off
	v_lshl_add_u64 v[206:207], s[52:53], 0, v[134:135]
	s_mov_b32 m0, s82
	s_nop 0
	global_load_lds_dwordx4 v[206:207], off
	s_waitcnt vmcnt(8)
	s_waitcnt lgkmcnt(0)
	s_barrier
	s_setprio 1
	s_waitcnt lgkmcnt(0)
	v_mfma_f32_16x16x32_bf16 v[126:129], v[142:145], v[188:191], v[126:129]
	v_mfma_f32_16x16x32_bf16 v[122:125], v[158:161], v[188:191], v[122:125]
	v_mfma_f32_16x16x32_bf16 v[110:113], v[142:145], v[196:199], v[110:113]
	v_mfma_f32_16x16x32_bf16 v[106:109], v[158:161], v[196:199], v[106:109]
	v_mfma_f32_16x16x32_bf16 v[94:97], v[142:145], v[216:219], v[94:97]
	v_mfma_f32_16x16x32_bf16 v[90:93], v[158:161], v[216:219], v[90:93]
	v_mfma_f32_16x16x32_bf16 v[78:81], v[142:145], v[224:227], v[78:81]
	v_mfma_f32_16x16x32_bf16 v[74:77], v[158:161], v[224:227], v[74:77]
	v_mfma_f32_16x16x32_bf16 v[126:129], v[148:151], v[192:195], v[126:129]
	v_mfma_f32_16x16x32_bf16 v[122:125], v[168:171], v[192:195], v[122:125]
	v_mfma_f32_16x16x32_bf16 v[110:113], v[148:151], v[208:211], v[110:113]
	v_mfma_f32_16x16x32_bf16 v[106:109], v[168:171], v[208:211], v[106:109]
	v_mfma_f32_16x16x32_bf16 v[94:97], v[148:151], v[220:223], v[94:97]
	v_mfma_f32_16x16x32_bf16 v[90:93], v[168:171], v[220:223], v[90:93]
	v_mfma_f32_16x16x32_bf16 v[78:81], v[148:151], v[228:231], v[78:81]
	v_mfma_f32_16x16x32_bf16 v[74:77], v[168:171], v[228:231], v[74:77]
	v_mfma_f32_16x16x32_bf16 v[118:121], v[172:175], v[188:191], v[118:121]
	v_mfma_f32_16x16x32_bf16 v[114:117], v[180:183], v[188:191], v[114:117]
	v_mfma_f32_16x16x32_bf16 v[102:105], v[172:175], v[196:199], v[102:105]
	v_mfma_f32_16x16x32_bf16 v[98:101], v[180:183], v[196:199], v[98:101]
	v_mfma_f32_16x16x32_bf16 v[86:89], v[172:175], v[216:219], v[86:89]
	v_mfma_f32_16x16x32_bf16 v[82:85], v[180:183], v[216:219], v[82:85]
	v_mfma_f32_16x16x32_bf16 v[70:73], v[172:175], v[224:227], v[70:73]
	v_mfma_f32_16x16x32_bf16 v[66:69], v[180:183], v[224:227], v[66:69]
	v_mfma_f32_16x16x32_bf16 v[118:121], v[176:179], v[192:195], v[118:121]
	v_mfma_f32_16x16x32_bf16 v[114:117], v[184:187], v[192:195], v[114:117]
	v_mfma_f32_16x16x32_bf16 v[102:105], v[176:179], v[208:211], v[102:105]
	v_mfma_f32_16x16x32_bf16 v[98:101], v[184:187], v[208:211], v[98:101]
	v_mfma_f32_16x16x32_bf16 v[86:89], v[176:179], v[220:223], v[86:89]
	v_mfma_f32_16x16x32_bf16 v[82:85], v[184:187], v[220:223], v[82:85]
	v_mfma_f32_16x16x32_bf16 v[70:73], v[176:179], v[228:231], v[70:73]
	v_mfma_f32_16x16x32_bf16 v[66:69], v[184:187], v[228:231], v[66:69]
	s_setprio 0
	s_barrier
; #define PG8_STAGE(bufoff, gbase, voff) do { _Pragma("unroll") for (int _i = 0; _i < 2; ++_i) \
;         __builtin_amdgcn_global_load_lds((const unsigned*)((const char*)(gbase) + (voff)[_i]), (PG8_LAS unsigned*)(lds + (bufoff) + ldsw + _i * 8192), 16, 0, 0); } while (0)
; #define PG8_LDA(dst, b, h) do { _Pragma("unroll") for (int m = 0; m < 4; ++m) _Pragma("unroll") for (int k = 0; k < 2; ++k) dst[m][k] = *(const PG8_LAS bf16x8*)(lds + PG8_SA(b, h) + aoff + m * 2048 + k * 1024); } while (0)
; #define PG8_WAIT_V(n) asm volatile("s_waitcnt vmcnt(" #n ")" ::: "memory")
; #define PG8_WAIT_L(n) asm volatile("s_waitcnt lgkmcnt(" #n ")" ::: "memory")
; #define PG8_BAR __builtin_amdgcn_s_barrier()
; #define PG8_SCHED __builtin_amdgcn_sched_barrier(0)
; template <class Epi, bool ALIGN_EPI = true>
; __device__ __forceinline__ void gemm_phase(PG8_LAS unsigned char* lds, const Gemm g, const StaticOrder& S, const Epi& E) {
;     ...
;         for (int t = 0; t < nt; t += 2) {
;             const bool last = (t == nt - 2);
;             const char* a1 = cA + (size_t)(t + 1) * kstep;
;             const char* a2 = last ? nA : cA + (size_t)(t + 2) * kstep; const char* b2 = last ? nB : cB + (size_t)(t + 2) * kstep;
;     ...
;             PG8_LDA(At, 1, 1); PG8_STAGE(PG8_SB(1, 0), b3, voffB); PG8_STAGE(PG8_SB(1, 1), b3 + hstepB, voffB); PG8_STAGE(PG8_SA(1, 0), a3, voffA);
;             PG8_WAIT_V(8); PG8_WAIT_L(0); PG8_BAR; PG8_MMA(1, 0, At, B0); PG8_MMA(1, 1, At, B1); PG8_BAR; PG8_SCHED;
	s_add_i32 s43, s43, s74
	v_lshl_add_u64 v[146:147], v[146:147], 0, s[60:61]
	s_mov_b32 m0, s43
	ds_read_b128 v[188:191], v167 offset:49152
	ds_read_b128 v[192:195], v167 offset:50176
	ds_read_b128 v[196:199], v167 offset:51200
	ds_read_b128 v[208:211], v167 offset:52224
	ds_read_b128 v[216:219], v167 offset:53248
	ds_read_b128 v[220:223], v167 offset:54272
	ds_read_b128 v[224:227], v167 offset:55296
	ds_read_b128 v[228:231], v167 offset:56320
	global_load_lds_dwordx4 v[146:147], off
	s_add_i32 m0, s43, 0x2000
	s_add_u32 s50, s50, 0x100080
	v_lshl_add_u64 v[146:147], v[162:163], 0, s[60:61]
	s_addc_u32 s51, s51, 0
	s_add_i32 s43, s93, s74
	global_load_lds_dwordx4 v[146:147], off
	v_lshl_add_u64 v[146:147], s[50:51], 0, v[132:133]
	s_mov_b32 m0, s43
	s_nop 0
	global_load_lds_dwordx4 v[146:147], off
	v_lshl_add_u64 v[146:147], s[50:51], 0, v[136:137]
	s_add_i32 m0, s43, 0x2000
	s_nop 0
	global_load_lds_dwordx4 v[146:147], off
	v_lshl_add_u64 v[146:147], v[200:201], 0, s[60:61]
	s_mov_b32 m0, s83
	s_nop 0
	global_load_lds_dwordx4 v[146:147], off
	v_lshl_add_u64 v[146:147], v[204:205], 0, s[60:61]
	s_mov_b32 m0, s85
	s_nop 0
	global_load_lds_dwordx4 v[146:147], off
	s_add_i32 s41, s41, 2
	s_add_u32 s48, s48, 0x100
	s_addc_u32 s49, s49, 0
	s_add_u32 s7, s7, 0x100
	s_addc_u32 s9, s9, 0
	s_add_u32 s43, s48, 0xfff00080
	s_addc_u32 s50, s49, -1
	s_add_i32 s93, 0, 0x10000
	s_cmp_eq_u32 s41, 60
	s_cselect_b32 s53, s45, s50
	s_cselect_b32 s52, s44, s43
	v_add_u32_e32 v32, s93, v165
	s_cselect_b32 s51, s47, s9
	s_cselect_b32 s50, s46, s7
	s_add_i32 s43, 0, 0x14000
	s_cmp_gt_u32 s41, 61
	s_waitcnt vmcnt(8)
	s_waitcnt lgkmcnt(0)
	s_barrier
	s_setprio 1
	s_waitcnt lgkmcnt(0)
	v_mfma_f32_16x16x32_bf16 v[62:65], v[142:145], v[188:191], v[62:65]
	v_mfma_f32_16x16x32_bf16 v[58:61], v[158:161], v[188:191], v[58:61]
	v_mfma_f32_16x16x32_bf16 v[46:49], v[142:145], v[196:199], v[46:49]
	v_mfma_f32_16x16x32_bf16 v[42:45], v[158:161], v[196:199], v[42:45]
	v_mfma_f32_16x16x32_bf16 v[28:31], v[142:145], v[216:219], v[28:31]
	v_mfma_f32_16x16x32_bf16 v[24:27], v[158:161], v[216:219], v[24:27]
	v_mfma_f32_16x16x32_bf16 v[12:15], v[142:145], v[224:227], v[12:15]
	v_mfma_f32_16x16x32_bf16 v[8:11], v[158:161], v[224:227], v[8:11]
	v_mfma_f32_16x16x32_bf16 v[62:65], v[148:151], v[192:195], v[62:65]
	v_mfma_f32_16x16x32_bf16 v[58:61], v[168:171], v[192:195], v[58:61]
	v_mfma_f32_16x16x32_bf16 v[46:49], v[148:151], v[208:211], v[46:49]
	v_mfma_f32_16x16x32_bf16 v[42:45], v[168:171], v[208:211], v[42:45]
	v_mfma_f32_16x16x32_bf16 v[28:31], v[148:151], v[220:223], v[28:31]
	v_mfma_f32_16x16x32_bf16 v[24:27], v[168:171], v[220:223], v[24:27]
	v_mfma_f32_16x16x32_bf16 v[12:15], v[148:151], v[228:231], v[12:15]
	v_mfma_f32_16x16x32_bf16 v[8:11], v[168:171], v[228:231], v[8:11]
	v_mfma_f32_16x16x32_bf16 v[54:57], v[172:175], v[188:191], v[54:57]
	v_mfma_f32_16x16x32_bf16 v[50:53], v[180:183], v[188:191], v[50:53]
	v_mfma_f32_16x16x32_bf16 v[38:41], v[172:175], v[196:199], v[38:41]
	v_mfma_f32_16x16x32_bf16 v[34:37], v[180:183], v[196:199], v[34:37]
	v_mfma_f32_16x16x32_bf16 v[20:23], v[172:175], v[216:219], v[20:23]
	v_mfma_f32_16x16x32_bf16 v[16:19], v[180:183], v[216:219], v[16:19]
	v_mfma_f32_16x16x32_bf16 v[4:7], v[172:175], v[224:227], v[4:7]
	v_mfma_f32_16x16x32_bf16 v[0:3], v[180:183], v[224:227], v[0:3]
	v_mfma_f32_16x16x32_bf16 v[54:57], v[176:179], v[192:195], v[54:57]
	v_mfma_f32_16x16x32_bf16 v[50:53], v[184:187], v[192:195], v[50:53]
	v_mfma_f32_16x16x32_bf16 v[38:41], v[176:179], v[208:211], v[38:41]
	v_mfma_f32_16x16x32_bf16 v[34:37], v[184:187], v[208:211], v[34:37]
	v_mfma_f32_16x16x32_bf16 v[20:23], v[176:179], v[220:223], v[20:23]
	v_mfma_f32_16x16x32_bf16 v[16:19], v[184:187], v[220:223], v[16:19]
	v_mfma_f32_16x16x32_bf16 v[4:7], v[176:179], v[228:231], v[4:7]
	v_mfma_f32_16x16x32_bf16 v[0:3], v[184:187], v[228:231], v[0:3]
	s_setprio 0
	s_barrier
	s_cbranch_scc0 .Lrot_2132
	s_and_b64 vcc, exec, s[38:39]
	s_cbranch_vccz .LBB0_2135
	s_barrier
